# combo12 + LDS ds_bpermute round trips replaced by v_permlane16/32_swap in CO LayerNorm reduce (xor32, xor16 levels) and in DN/WO/PL row-statistics all-reduce; bit-identical
# baseline (speedup 1.0000x reference)
.LBB0_58:
	v_cvt_pk_bf16_f32 v152, v120, v121
	v_mul_f32_e32 v121, v121, v121
	v_fmac_f32_e32 v121, v120, v120
	v_mul_f32_e32 v120, v123, v123
	v_fmac_f32_e32 v120, v122, v122
	v_cvt_pk_bf16_f32 v153, v122, v123
	v_add_f32_e32 v120, v121, v120
	v_mul_f32_e32 v121, v129, v129
	v_mul_f32_e32 v122, v131, v131
	v_fmac_f32_e32 v121, v128, v128
	v_fmac_f32_e32 v122, v130, v130
	v_add_f32_e32 v121, v121, v122
	v_add_f32_e32 v120, v121, v120
	v_mul_f32_e32 v121, v117, v117
	v_mul_f32_e32 v122, v119, v119
	v_fmac_f32_e32 v121, v116, v116
	v_fmac_f32_e32 v122, v118, v118
	v_add_f32_e32 v121, v121, v122
	v_mul_f32_e32 v122, v125, v125
	v_mul_f32_e32 v123, v127, v127
	v_fmac_f32_e32 v122, v124, v124
	v_fmac_f32_e32 v123, v126, v126
	v_add_f32_e32 v122, v122, v123
	v_add_f32_e32 v121, v122, v121
	v_add_f32_e32 v121, v121, v120
	v_and_or_b32 v120, v1, 64, v148
	v_cvt_pk_bf16_f32 v154, v128, v129
	v_cvt_pk_bf16_f32 v155, v130, v131
	v_lshlrev_b32_e32 v130, 2, v120
	v_xor_b32_e32 v120, 64, v130
	v_lshl_add_u32 v144, s37, 8, v146
	v_mov_b32_e32 v131, v121
	s_nop 1
	v_permlane16_swap_b32_e32 v131, v121
	v_ashrrev_i32_e32 v145, 31, v144
	v_readlane_b32 s20, v251, 34
	v_lshl_or_b32 v142, s36, 8, v149
	v_lshlrev_b64 v[156:157], 11, v[144:145]
	v_readlane_b32 s21, v251, 35
	v_ashrrev_i32_e32 v143, 31, v142
	s_lshl_b32 s18, s36, 2
	v_lshl_add_u64 v[122:123], s[20:21], 0, v[156:157]
	v_lshl_add_u64 v[128:129], v[142:143], 1, v[122:123]
	global_store_dwordx4 v[128:129], v[152:155], off
	v_cvt_pk_bf16_f32 v122, v116, v117
	s_waitcnt lgkmcnt(0)
	v_add_f32_e32 v116, v121, v131
	v_xor_b32_e32 v121, 0x80, v130
	v_mov_b32_e32 v117, v116
	s_nop 1
	v_permlane32_swap_b32_e32 v117, v116
	s_ashr_i32 s19, s18, 31
	v_cvt_pk_bf16_f32 v123, v118, v119
	v_cvt_pk_bf16_f32 v124, v124, v125
	v_cvt_pk_bf16_f32 v125, v126, v127
	global_store_dwordx4 v[128:129], v[122:125], off offset:256
	s_and_saveexec_b64 s[20:21], s[38:39]
	s_cbranch_execz .LBB0_60
	v_readlane_b32 s36, v254, 58
	v_lshlrev_b64 v[118:119], 6, v[144:145]
	v_readlane_b32 s37, v254, 59
	s_lshl_b32 s44, s15, 2
	s_waitcnt lgkmcnt(0)
	v_add_f32_e32 v116, v116, v117
	v_lshl_add_u64 v[118:119], s[36:37], 0, v[118:119]
	v_readlane_b32 s36, v254, 4
	v_readlane_b32 s37, v254, 5
	v_lshl_add_u64 v[118:119], s[18:19], 2, v[118:119]
	s_mov_b32 s45, s37
	v_writelane_b32 v254, s36, 4
	v_lshl_add_u64 v[118:119], v[118:119], 0, s[44:45]
	global_store_dword v[118:119], v116, off
	v_writelane_b32 v254, s37, 5
.LBB0_60:
	s_or_b64 exec, exec, s[20:21]
	v_cvt_pk_bf16_f32 v122, v104, v105
	v_mul_f32_e32 v105, v105, v105
	v_fmac_f32_e32 v105, v104, v104
	v_mul_f32_e32 v104, v107, v107
	v_fmac_f32_e32 v104, v106, v106
	v_cvt_pk_bf16_f32 v123, v106, v107
	v_add_f32_e32 v104, v105, v104
	v_mul_f32_e32 v105, v113, v113
	v_mul_f32_e32 v106, v115, v115
	v_fmac_f32_e32 v105, v112, v112
	v_fmac_f32_e32 v106, v114, v114
	v_add_f32_e32 v105, v105, v106
	v_add_f32_e32 v104, v105, v104
	v_mul_f32_e32 v105, v101, v101
	v_mul_f32_e32 v106, v103, v103
	v_fmac_f32_e32 v105, v100, v100
	v_fmac_f32_e32 v106, v102, v102
	v_add_f32_e32 v105, v105, v106
	v_mul_f32_e32 v106, v109, v109
	v_mul_f32_e32 v107, v111, v111
	v_fmac_f32_e32 v106, v108, v108
	v_fmac_f32_e32 v107, v110, v110
	v_add_f32_e32 v106, v106, v107
	v_add_f32_e32 v105, v106, v105
	v_add_f32_e32 v106, v105, v104
	v_or_b32_e32 v116, 16, v144
	v_mov_b32_e32 v107, v106
	s_nop 1
	v_permlane16_swap_b32_e32 v107, v106
	s_waitcnt lgkmcnt(0)
	v_ashrrev_i32_e32 v117, 31, v116
	v_readlane_b32 s20, v251, 34
	v_lshlrev_b64 v[118:119], 11, v[116:117]
	v_readlane_b32 s21, v251, 35
	v_cvt_pk_bf16_f32 v124, v112, v113
	v_cvt_pk_bf16_f32 v125, v114, v115
	s_nop 1
	v_lshl_add_u64 v[104:105], s[20:21], 0, v[118:119]
	v_lshl_add_u64 v[112:113], v[142:143], 1, v[104:105]
	global_store_dwordx4 v[112:113], v[122:125], off
	v_cvt_pk_bf16_f32 v104, v100, v101
	v_add_f32_e32 v100, v106, v107
	v_mov_b32_e32 v101, v100
	s_nop 1
	v_permlane32_swap_b32_e32 v101, v100
	v_cvt_pk_bf16_f32 v105, v102, v103
	v_cvt_pk_bf16_f32 v106, v108, v109
	v_cvt_pk_bf16_f32 v107, v110, v111
	global_store_dwordx4 v[112:113], v[104:107], off offset:256
	s_and_saveexec_b64 s[20:21], s[38:39]
	s_cbranch_execz .LBB0_62
	v_readlane_b32 s36, v254, 58
	v_lshlrev_b64 v[102:103], 6, v[116:117]
	v_readlane_b32 s37, v254, 59
	s_lshl_b32 s44, s15, 2
	s_waitcnt lgkmcnt(0)
	v_add_f32_e32 v100, v100, v101
	v_lshl_add_u64 v[102:103], s[36:37], 0, v[102:103]
	v_readlane_b32 s36, v254, 4
	v_readlane_b32 s37, v254, 5
	v_lshl_add_u64 v[102:103], s[18:19], 2, v[102:103]
	s_mov_b32 s45, s37
	v_writelane_b32 v254, s36, 4
	v_lshl_add_u64 v[102:103], v[102:103], 0, s[44:45]
	global_store_dword v[102:103], v100, off
	v_writelane_b32 v254, s37, 5
.LBB0_62:
	s_or_b64 exec, exec, s[20:21]
	v_cvt_pk_bf16_f32 v102, v88, v89
	v_mul_f32_e32 v89, v89, v89
	v_fmac_f32_e32 v89, v88, v88
	v_mul_f32_e32 v88, v91, v91
	v_fmac_f32_e32 v88, v90, v90
	v_cvt_pk_bf16_f32 v103, v90, v91
	v_add_f32_e32 v88, v89, v88
	v_mul_f32_e32 v89, v97, v97
	v_mul_f32_e32 v90, v99, v99
	v_fmac_f32_e32 v89, v96, v96
	v_fmac_f32_e32 v90, v98, v98
	v_add_f32_e32 v89, v89, v90
	v_add_f32_e32 v88, v89, v88
	v_mul_f32_e32 v89, v85, v85
	v_mul_f32_e32 v90, v87, v87
	v_fmac_f32_e32 v89, v84, v84
	v_fmac_f32_e32 v90, v86, v86
	v_add_f32_e32 v89, v89, v90
	v_mul_f32_e32 v90, v93, v93
	v_mul_f32_e32 v91, v95, v95
	v_fmac_f32_e32 v90, v92, v92
	v_fmac_f32_e32 v91, v94, v94
	v_add_f32_e32 v90, v90, v91
	v_add_f32_e32 v89, v90, v89
	v_add_f32_e32 v90, v89, v88
	v_or_b32_e32 v100, 32, v144
	v_mov_b32_e32 v91, v90
	s_nop 1
	v_permlane16_swap_b32_e32 v91, v90
	s_waitcnt lgkmcnt(0)
	v_ashrrev_i32_e32 v101, 31, v100
	v_readlane_b32 s20, v251, 34
	v_lshlrev_b64 v[106:107], 11, v[100:101]
	v_readlane_b32 s21, v251, 35
	v_cvt_pk_bf16_f32 v104, v96, v97
	v_cvt_pk_bf16_f32 v105, v98, v99
	s_nop 1
	v_lshl_add_u64 v[88:89], s[20:21], 0, v[106:107]
	v_lshl_add_u64 v[96:97], v[142:143], 1, v[88:89]
	global_store_dwordx4 v[96:97], v[102:105], off
	v_cvt_pk_bf16_f32 v88, v84, v85
	v_add_f32_e32 v84, v90, v91
	v_mov_b32_e32 v85, v84
	s_nop 1
	v_permlane32_swap_b32_e32 v85, v84
	v_cvt_pk_bf16_f32 v89, v86, v87
	v_cvt_pk_bf16_f32 v90, v92, v93
	v_cvt_pk_bf16_f32 v91, v94, v95
	global_store_dwordx4 v[96:97], v[88:91], off offset:256
	s_and_saveexec_b64 s[20:21], s[38:39]
	s_cbranch_execz .LBB0_64
	v_readlane_b32 s36, v254, 58
	v_lshlrev_b64 v[86:87], 6, v[100:101]
	v_readlane_b32 s37, v254, 59
	s_lshl_b32 s44, s15, 2
	s_waitcnt lgkmcnt(0)
	v_add_f32_e32 v84, v84, v85
	v_lshl_add_u64 v[86:87], s[36:37], 0, v[86:87]
	v_readlane_b32 s36, v254, 4
	v_readlane_b32 s37, v254, 5
	v_lshl_add_u64 v[86:87], s[18:19], 2, v[86:87]
	s_mov_b32 s45, s37
	v_writelane_b32 v254, s36, 4
	v_lshl_add_u64 v[86:87], v[86:87], 0, s[44:45]
	global_store_dword v[86:87], v84, off
	v_writelane_b32 v254, s37, 5
.LBB0_64:
	s_or_b64 exec, exec, s[20:21]
	v_cvt_pk_bf16_f32 v86, v72, v73
	v_mul_f32_e32 v73, v73, v73
	v_fmac_f32_e32 v73, v72, v72
	v_mul_f32_e32 v72, v75, v75
	v_fmac_f32_e32 v72, v74, v74
	v_cvt_pk_bf16_f32 v87, v74, v75
	v_add_f32_e32 v72, v73, v72
	v_mul_f32_e32 v73, v81, v81
	v_mul_f32_e32 v74, v83, v83
	v_fmac_f32_e32 v73, v80, v80
	v_fmac_f32_e32 v74, v82, v82
	v_add_f32_e32 v73, v73, v74
	v_add_f32_e32 v72, v73, v72
	v_mul_f32_e32 v73, v69, v69
	v_mul_f32_e32 v74, v71, v71
	v_fmac_f32_e32 v73, v68, v68
	v_fmac_f32_e32 v74, v70, v70
	v_add_f32_e32 v73, v73, v74
	v_mul_f32_e32 v74, v77, v77
	v_mul_f32_e32 v75, v79, v79
	v_fmac_f32_e32 v74, v76, v76
	v_fmac_f32_e32 v75, v78, v78
	v_add_f32_e32 v74, v74, v75
	v_add_f32_e32 v73, v74, v73
	v_add_f32_e32 v74, v73, v72
	v_or_b32_e32 v84, 48, v144
	v_mov_b32_e32 v75, v74
	s_nop 1
	v_permlane16_swap_b32_e32 v75, v74
	s_waitcnt lgkmcnt(0)
	v_ashrrev_i32_e32 v85, 31, v84
	v_readlane_b32 s20, v251, 34
	v_lshlrev_b64 v[90:91], 11, v[84:85]
	v_readlane_b32 s21, v251, 35
	v_cvt_pk_bf16_f32 v88, v80, v81
	v_cvt_pk_bf16_f32 v89, v82, v83
	s_nop 1
	v_lshl_add_u64 v[72:73], s[20:21], 0, v[90:91]
	v_lshl_add_u64 v[80:81], v[142:143], 1, v[72:73]
	global_store_dwordx4 v[80:81], v[86:89], off
	v_cvt_pk_bf16_f32 v72, v68, v69
	v_add_f32_e32 v68, v74, v75
	v_mov_b32_e32 v69, v68
	s_nop 1
	v_permlane32_swap_b32_e32 v69, v68
	v_cvt_pk_bf16_f32 v73, v70, v71
	v_cvt_pk_bf16_f32 v74, v76, v77
	v_cvt_pk_bf16_f32 v75, v78, v79
	global_store_dwordx4 v[80:81], v[72:75], off offset:256
	s_and_saveexec_b64 s[20:21], s[38:39]
	s_cbranch_execz .LBB0_66
	v_readlane_b32 s36, v254, 58
	v_lshlrev_b64 v[70:71], 6, v[84:85]
	v_readlane_b32 s37, v254, 59
	s_lshl_b32 s44, s15, 2
	s_waitcnt lgkmcnt(0)
	v_add_f32_e32 v68, v68, v69
	v_lshl_add_u64 v[70:71], s[36:37], 0, v[70:71]
	v_readlane_b32 s36, v254, 4
	v_readlane_b32 s37, v254, 5
	v_lshl_add_u64 v[70:71], s[18:19], 2, v[70:71]
	s_mov_b32 s45, s37
	v_writelane_b32 v254, s36, 4
	v_lshl_add_u64 v[70:71], v[70:71], 0, s[44:45]
	global_store_dword v[70:71], v68, off
	v_writelane_b32 v254, s37, 5
.LBB0_66:
	s_or_b64 exec, exec, s[20:21]
	v_cvt_pk_bf16_f32 v70, v56, v57
	v_mul_f32_e32 v57, v57, v57
	v_fmac_f32_e32 v57, v56, v56
	v_mul_f32_e32 v56, v59, v59
	v_fmac_f32_e32 v56, v58, v58
	v_cvt_pk_bf16_f32 v71, v58, v59
	v_add_f32_e32 v56, v57, v56
	v_mul_f32_e32 v57, v65, v65
	v_mul_f32_e32 v58, v67, v67
	v_fmac_f32_e32 v57, v64, v64
	v_fmac_f32_e32 v58, v66, v66
	v_add_f32_e32 v57, v57, v58
	v_add_f32_e32 v56, v57, v56
	v_mul_f32_e32 v57, v53, v53
	v_mul_f32_e32 v58, v55, v55
	v_fmac_f32_e32 v57, v52, v52
	v_fmac_f32_e32 v58, v54, v54
	v_add_f32_e32 v57, v57, v58
	v_mul_f32_e32 v58, v61, v61
	v_mul_f32_e32 v59, v63, v63
	v_fmac_f32_e32 v58, v60, v60
	v_fmac_f32_e32 v59, v62, v62
	v_add_f32_e32 v58, v58, v59
	v_add_f32_e32 v57, v58, v57
	v_add_f32_e32 v58, v57, v56
	v_add_u32_e32 v68, 0x80, v144
	v_mov_b32_e32 v59, v58
	s_nop 1
	v_permlane16_swap_b32_e32 v59, v58
	s_waitcnt lgkmcnt(0)
	v_ashrrev_i32_e32 v69, 31, v68
	v_readlane_b32 s20, v251, 34
	v_lshlrev_b64 v[74:75], 11, v[68:69]
	v_readlane_b32 s21, v251, 35
	v_cvt_pk_bf16_f32 v72, v64, v65
	v_cvt_pk_bf16_f32 v73, v66, v67
	s_nop 1
	v_lshl_add_u64 v[56:57], s[20:21], 0, v[74:75]
	v_lshl_add_u64 v[64:65], v[142:143], 1, v[56:57]
	global_store_dwordx4 v[64:65], v[70:73], off
	v_cvt_pk_bf16_f32 v56, v52, v53
	v_add_f32_e32 v52, v58, v59
	v_mov_b32_e32 v53, v52
	s_nop 1
	v_permlane32_swap_b32_e32 v53, v52
	v_cvt_pk_bf16_f32 v57, v54, v55
	v_cvt_pk_bf16_f32 v58, v60, v61
	v_cvt_pk_bf16_f32 v59, v62, v63
	global_store_dwordx4 v[64:65], v[56:59], off offset:256
	s_and_saveexec_b64 s[20:21], s[38:39]
	s_cbranch_execz .LBB0_68
	v_readlane_b32 s36, v254, 58
	v_lshlrev_b64 v[54:55], 6, v[68:69]
	v_readlane_b32 s37, v254, 59
	s_lshl_b32 s44, s15, 2
	s_waitcnt lgkmcnt(0)
	v_add_f32_e32 v52, v52, v53
	v_lshl_add_u64 v[54:55], s[36:37], 0, v[54:55]
	v_readlane_b32 s36, v254, 4
	v_readlane_b32 s37, v254, 5
	v_lshl_add_u64 v[54:55], s[18:19], 2, v[54:55]
	s_mov_b32 s45, s37
	v_writelane_b32 v254, s36, 4
	v_lshl_add_u64 v[54:55], v[54:55], 0, s[44:45]
	global_store_dword v[54:55], v52, off
	v_writelane_b32 v254, s37, 5
.LBB0_68:
	s_or_b64 exec, exec, s[20:21]
	v_cvt_pk_bf16_f32 v54, v40, v41
	v_mul_f32_e32 v41, v41, v41
	v_fmac_f32_e32 v41, v40, v40
	v_mul_f32_e32 v40, v43, v43
	v_fmac_f32_e32 v40, v42, v42
	v_cvt_pk_bf16_f32 v55, v42, v43
	v_add_f32_e32 v40, v41, v40
	v_mul_f32_e32 v41, v49, v49
	v_mul_f32_e32 v42, v51, v51
	v_fmac_f32_e32 v41, v48, v48
	v_fmac_f32_e32 v42, v50, v50
	v_add_f32_e32 v41, v41, v42
	v_add_f32_e32 v40, v41, v40
	v_mul_f32_e32 v41, v37, v37
	v_mul_f32_e32 v42, v39, v39
	v_fmac_f32_e32 v41, v36, v36
	v_fmac_f32_e32 v42, v38, v38
	v_add_f32_e32 v41, v41, v42
	v_mul_f32_e32 v42, v45, v45
	v_mul_f32_e32 v43, v47, v47
	v_fmac_f32_e32 v42, v44, v44
	v_fmac_f32_e32 v43, v46, v46
	v_add_f32_e32 v42, v42, v43
	v_add_f32_e32 v41, v42, v41
	v_add_f32_e32 v42, v41, v40
	v_add_u32_e32 v52, 0x90, v144
	v_mov_b32_e32 v43, v42
	s_nop 1
	v_permlane16_swap_b32_e32 v43, v42
	s_waitcnt lgkmcnt(0)
	v_ashrrev_i32_e32 v53, 31, v52
	v_readlane_b32 s20, v251, 34
	v_lshlrev_b64 v[58:59], 11, v[52:53]
	v_readlane_b32 s21, v251, 35
	v_cvt_pk_bf16_f32 v56, v48, v49
	v_cvt_pk_bf16_f32 v57, v50, v51
	s_nop 1
	v_lshl_add_u64 v[40:41], s[20:21], 0, v[58:59]
	v_lshl_add_u64 v[48:49], v[142:143], 1, v[40:41]
	global_store_dwordx4 v[48:49], v[54:57], off
	v_cvt_pk_bf16_f32 v40, v36, v37
	v_add_f32_e32 v36, v42, v43
	v_mov_b32_e32 v37, v36
	s_nop 1
	v_permlane32_swap_b32_e32 v37, v36
	v_cvt_pk_bf16_f32 v41, v38, v39
	v_cvt_pk_bf16_f32 v42, v44, v45
	v_cvt_pk_bf16_f32 v43, v46, v47
	global_store_dwordx4 v[48:49], v[40:43], off offset:256
	s_and_saveexec_b64 s[20:21], s[38:39]
	s_cbranch_execz .LBB0_70
	v_readlane_b32 s36, v254, 58
	v_lshlrev_b64 v[38:39], 6, v[52:53]
	v_readlane_b32 s37, v254, 59
	s_lshl_b32 s44, s15, 2
	s_waitcnt lgkmcnt(0)
	v_add_f32_e32 v36, v36, v37
	v_lshl_add_u64 v[38:39], s[36:37], 0, v[38:39]
	v_readlane_b32 s36, v254, 4
	v_readlane_b32 s37, v254, 5
	v_lshl_add_u64 v[38:39], s[18:19], 2, v[38:39]
	s_mov_b32 s45, s37
	v_writelane_b32 v254, s36, 4
	v_lshl_add_u64 v[38:39], v[38:39], 0, s[44:45]
	global_store_dword v[38:39], v36, off
	v_writelane_b32 v254, s37, 5
.LBB0_70:
	s_or_b64 exec, exec, s[20:21]
	v_cvt_pk_bf16_f32 v38, v24, v25
	v_mul_f32_e32 v25, v25, v25
	v_fmac_f32_e32 v25, v24, v24
	v_mul_f32_e32 v24, v27, v27
	v_fmac_f32_e32 v24, v26, v26
	v_cvt_pk_bf16_f32 v39, v26, v27
	v_add_f32_e32 v24, v25, v24
	v_mul_f32_e32 v25, v33, v33
	v_mul_f32_e32 v26, v35, v35
	v_fmac_f32_e32 v25, v32, v32
	v_fmac_f32_e32 v26, v34, v34
	v_add_f32_e32 v25, v25, v26
	v_add_f32_e32 v24, v25, v24
	v_mul_f32_e32 v25, v21, v21
	v_mul_f32_e32 v26, v23, v23
	v_fmac_f32_e32 v25, v20, v20
	v_fmac_f32_e32 v26, v22, v22
	v_add_f32_e32 v25, v25, v26
	v_mul_f32_e32 v26, v29, v29
	v_mul_f32_e32 v27, v31, v31
	v_fmac_f32_e32 v26, v28, v28
	v_fmac_f32_e32 v27, v30, v30
	v_add_f32_e32 v26, v26, v27
	v_add_f32_e32 v25, v26, v25
	v_add_f32_e32 v26, v25, v24
	v_add_u32_e32 v36, 0xa0, v144
	v_mov_b32_e32 v27, v26
	s_nop 1
	v_permlane16_swap_b32_e32 v27, v26
	s_waitcnt lgkmcnt(0)
	v_ashrrev_i32_e32 v37, 31, v36
	v_readlane_b32 s20, v251, 34
	v_lshlrev_b64 v[42:43], 11, v[36:37]
	v_readlane_b32 s21, v251, 35
	v_cvt_pk_bf16_f32 v40, v32, v33
	v_cvt_pk_bf16_f32 v41, v34, v35
	s_nop 1
	v_lshl_add_u64 v[24:25], s[20:21], 0, v[42:43]
	v_lshl_add_u64 v[32:33], v[142:143], 1, v[24:25]
	global_store_dwordx4 v[32:33], v[38:41], off
	v_cvt_pk_bf16_f32 v24, v20, v21
	v_add_f32_e32 v20, v26, v27
	v_mov_b32_e32 v21, v20
	s_nop 1
	v_permlane32_swap_b32_e32 v21, v20
	v_cvt_pk_bf16_f32 v25, v22, v23
	v_cvt_pk_bf16_f32 v26, v28, v29
	v_cvt_pk_bf16_f32 v27, v30, v31
	global_store_dwordx4 v[32:33], v[24:27], off offset:256
	s_and_saveexec_b64 s[20:21], s[38:39]
	s_cbranch_execz .LBB0_72
	v_readlane_b32 s36, v254, 58
	v_lshlrev_b64 v[22:23], 6, v[36:37]
	v_readlane_b32 s37, v254, 59
	s_lshl_b32 s44, s15, 2
	s_waitcnt lgkmcnt(0)
	v_add_f32_e32 v20, v20, v21
	v_lshl_add_u64 v[22:23], s[36:37], 0, v[22:23]
	v_readlane_b32 s36, v254, 4
	v_readlane_b32 s37, v254, 5
	v_lshl_add_u64 v[22:23], s[18:19], 2, v[22:23]
	s_mov_b32 s45, s37
	v_writelane_b32 v254, s36, 4
	v_lshl_add_u64 v[22:23], v[22:23], 0, s[44:45]
	global_store_dword v[22:23], v20, off
	v_writelane_b32 v254, s37, 5
.LBB0_72:
	s_or_b64 exec, exec, s[20:21]
	v_cvt_pk_bf16_f32 v22, v8, v9
	v_mul_f32_e32 v9, v9, v9
	v_fmac_f32_e32 v9, v8, v8
	v_mul_f32_e32 v8, v11, v11
	v_fmac_f32_e32 v8, v10, v10
	v_cvt_pk_bf16_f32 v23, v10, v11
	v_add_f32_e32 v8, v9, v8
	v_mul_f32_e32 v9, v17, v17
	v_mul_f32_e32 v10, v19, v19
	v_fmac_f32_e32 v9, v16, v16
	v_fmac_f32_e32 v10, v18, v18
	v_add_f32_e32 v9, v9, v10
	v_add_f32_e32 v8, v9, v8
	v_mul_f32_e32 v9, v5, v5
	v_mul_f32_e32 v10, v7, v7
	v_fmac_f32_e32 v9, v4, v4
	v_fmac_f32_e32 v10, v6, v6
	v_add_f32_e32 v9, v9, v10
	v_mul_f32_e32 v10, v13, v13
	v_mul_f32_e32 v11, v15, v15
	v_fmac_f32_e32 v10, v12, v12
	v_fmac_f32_e32 v11, v14, v14
	v_add_f32_e32 v10, v10, v11
	v_add_f32_e32 v9, v10, v9
	v_add_f32_e32 v10, v9, v8
	v_add_u32_e32 v20, 0xb0, v144
	v_mov_b32_e32 v11, v10
	s_nop 1
	v_permlane16_swap_b32_e32 v11, v10
	s_waitcnt lgkmcnt(0)
	v_ashrrev_i32_e32 v21, 31, v20
	v_readlane_b32 s20, v251, 34
	v_lshlrev_b64 v[26:27], 11, v[20:21]
	v_readlane_b32 s21, v251, 35
	v_cvt_pk_bf16_f32 v24, v16, v17
	v_cvt_pk_bf16_f32 v25, v18, v19
	s_nop 1
	v_lshl_add_u64 v[8:9], s[20:21], 0, v[26:27]
	v_lshl_add_u64 v[16:17], v[142:143], 1, v[8:9]
	global_store_dwordx4 v[16:17], v[22:25], off
	v_cvt_pk_bf16_f32 v8, v4, v5
	v_add_f32_e32 v4, v10, v11
	v_mov_b32_e32 v5, v4
	s_nop 1
	v_permlane32_swap_b32_e32 v5, v4
	v_cvt_pk_bf16_f32 v9, v6, v7
	v_cvt_pk_bf16_f32 v10, v12, v13
	v_cvt_pk_bf16_f32 v11, v14, v15
	global_store_dwordx4 v[16:17], v[8:11], off offset:256
	s_and_saveexec_b64 s[20:21], s[38:39]
	s_cbranch_execz .LBB0_74
	v_readlane_b32 s36, v254, 58
	v_lshlrev_b64 v[6:7], 6, v[20:21]
	v_readlane_b32 s37, v254, 59
	s_waitcnt lgkmcnt(0)
	v_add_f32_e32 v4, v4, v5
	v_lshl_add_u64 v[6:7], s[36:37], 0, v[6:7]
	v_lshl_add_u64 v[6:7], s[18:19], 2, v[6:7]
	v_readlane_b32 s18, v254, 4
	v_readlane_b32 s19, v254, 5
	s_mov_b32 s37, s19
	s_lshl_b32 s36, s15, 2
	v_writelane_b32 v254, s18, 4
	v_lshl_add_u64 v[6:7], v[6:7], 0, s[36:37]
	global_store_dword v[6:7], v4, off
	v_writelane_b32 v254, s19, 5

.LBB0_222:
	v_cvt_pk_bf16_f32 v152, v120, v121
	v_mul_f32_e32 v121, v121, v121
	v_fmac_f32_e32 v121, v120, v120
	v_mul_f32_e32 v120, v123, v123
	v_fmac_f32_e32 v120, v122, v122
	v_cvt_pk_bf16_f32 v153, v122, v123
	v_add_f32_e32 v120, v121, v120
	v_mul_f32_e32 v121, v129, v129
	v_mul_f32_e32 v122, v131, v131
	v_fmac_f32_e32 v121, v128, v128
	v_fmac_f32_e32 v122, v130, v130
	v_add_f32_e32 v121, v121, v122
	v_add_f32_e32 v120, v121, v120
	v_mul_f32_e32 v121, v117, v117
	v_mul_f32_e32 v122, v119, v119
	v_fmac_f32_e32 v121, v116, v116
	v_fmac_f32_e32 v122, v118, v118
	v_add_f32_e32 v121, v121, v122
	v_mul_f32_e32 v122, v125, v125
	v_mul_f32_e32 v123, v127, v127
	v_fmac_f32_e32 v122, v124, v124
	v_fmac_f32_e32 v123, v126, v126
	v_add_f32_e32 v122, v122, v123
	v_add_f32_e32 v121, v122, v121
	v_add_f32_e32 v121, v121, v120
	v_xor_b32_e32 v120, 64, v150
	v_lshl_add_u32 v144, s47, 8, v146
	v_cvt_pk_bf16_f32 v154, v128, v129
	v_cvt_pk_bf16_f32 v155, v130, v131
	v_mov_b32_e32 v130, v121
	s_nop 1
	v_permlane16_swap_b32_e32 v130, v121
	v_ashrrev_i32_e32 v145, 31, v144
	v_readlane_b32 s22, v251, 34
	v_lshl_or_b32 v142, s46, 8, v148
	v_lshlrev_b64 v[156:157], 11, v[144:145]
	v_readlane_b32 s23, v251, 35
	v_ashrrev_i32_e32 v143, 31, v142
	s_lshl_b32 s20, s46, 2
	v_lshl_add_u64 v[122:123], s[22:23], 0, v[156:157]
	v_lshl_add_u64 v[128:129], v[142:143], 1, v[122:123]
	global_store_dwordx4 v[128:129], v[152:155], off
	v_cvt_pk_bf16_f32 v122, v116, v117
	s_waitcnt lgkmcnt(0)
	v_add_f32_e32 v116, v121, v130
	v_xor_b32_e32 v121, 0x80, v150
	v_mov_b32_e32 v117, v116
	s_nop 1
	v_permlane32_swap_b32_e32 v117, v116
	s_ashr_i32 s21, s20, 31
	v_cvt_pk_bf16_f32 v123, v118, v119
	v_cvt_pk_bf16_f32 v124, v124, v125
	v_cvt_pk_bf16_f32 v125, v126, v127
	global_store_dwordx4 v[128:129], v[122:125], off offset:256
	s_and_saveexec_b64 s[22:23], s[38:39]
	s_cbranch_execz .LBB0_224
	v_readlane_b32 s46, v254, 60
	v_lshlrev_b64 v[118:119], 6, v[144:145]
	v_readlane_b32 s47, v254, 61
	s_lshl_b32 s48, s25, 2
	s_waitcnt lgkmcnt(0)
	v_add_f32_e32 v116, v116, v117
	v_lshl_add_u64 v[118:119], s[46:47], 0, v[118:119]
	v_readlane_b32 s46, v254, 4
	v_readlane_b32 s47, v254, 5
	v_lshl_add_u64 v[118:119], s[20:21], 2, v[118:119]
	s_mov_b32 s49, s47
	v_writelane_b32 v254, s46, 4
	v_lshl_add_u64 v[118:119], v[118:119], 0, s[48:49]
	global_store_dword v[118:119], v116, off
	v_writelane_b32 v254, s47, 5
.LBB0_224:
	s_or_b64 exec, exec, s[22:23]
	v_cvt_pk_bf16_f32 v122, v104, v105
	v_mul_f32_e32 v105, v105, v105
	v_fmac_f32_e32 v105, v104, v104
	v_mul_f32_e32 v104, v107, v107
	v_fmac_f32_e32 v104, v106, v106
	v_cvt_pk_bf16_f32 v123, v106, v107
	v_add_f32_e32 v104, v105, v104
	v_mul_f32_e32 v105, v113, v113
	v_mul_f32_e32 v106, v115, v115
	v_fmac_f32_e32 v105, v112, v112
	v_fmac_f32_e32 v106, v114, v114
	v_add_f32_e32 v105, v105, v106
	v_add_f32_e32 v104, v105, v104
	v_mul_f32_e32 v105, v101, v101
	v_mul_f32_e32 v106, v103, v103
	v_fmac_f32_e32 v105, v100, v100
	v_fmac_f32_e32 v106, v102, v102
	v_add_f32_e32 v105, v105, v106
	v_mul_f32_e32 v106, v109, v109
	v_mul_f32_e32 v107, v111, v111
	v_fmac_f32_e32 v106, v108, v108
	v_fmac_f32_e32 v107, v110, v110
	v_add_f32_e32 v106, v106, v107
	v_add_f32_e32 v105, v106, v105
	v_add_f32_e32 v106, v105, v104
	v_or_b32_e32 v116, 16, v144
	v_mov_b32_e32 v107, v106
	s_nop 1
	v_permlane16_swap_b32_e32 v107, v106
	s_waitcnt lgkmcnt(0)
	v_ashrrev_i32_e32 v117, 31, v116
	v_readlane_b32 s22, v251, 34
	v_lshlrev_b64 v[118:119], 11, v[116:117]
	v_readlane_b32 s23, v251, 35
	v_cvt_pk_bf16_f32 v124, v112, v113
	v_cvt_pk_bf16_f32 v125, v114, v115
	s_nop 1
	v_lshl_add_u64 v[104:105], s[22:23], 0, v[118:119]
	v_lshl_add_u64 v[112:113], v[142:143], 1, v[104:105]
	global_store_dwordx4 v[112:113], v[122:125], off
	v_cvt_pk_bf16_f32 v104, v100, v101
	v_add_f32_e32 v100, v106, v107
	v_mov_b32_e32 v101, v100
	s_nop 1
	v_permlane32_swap_b32_e32 v101, v100
	v_cvt_pk_bf16_f32 v105, v102, v103
	v_cvt_pk_bf16_f32 v106, v108, v109
	v_cvt_pk_bf16_f32 v107, v110, v111
	global_store_dwordx4 v[112:113], v[104:107], off offset:256
	s_and_saveexec_b64 s[22:23], s[38:39]
	s_cbranch_execz .LBB0_226
	v_readlane_b32 s46, v254, 60
	v_lshlrev_b64 v[102:103], 6, v[116:117]
	v_readlane_b32 s47, v254, 61
	s_lshl_b32 s48, s25, 2
	s_waitcnt lgkmcnt(0)
	v_add_f32_e32 v100, v100, v101
	v_lshl_add_u64 v[102:103], s[46:47], 0, v[102:103]
	v_readlane_b32 s46, v254, 4
	v_readlane_b32 s47, v254, 5
	v_lshl_add_u64 v[102:103], s[20:21], 2, v[102:103]
	s_mov_b32 s49, s47
	v_writelane_b32 v254, s46, 4
	v_lshl_add_u64 v[102:103], v[102:103], 0, s[48:49]
	global_store_dword v[102:103], v100, off
	v_writelane_b32 v254, s47, 5
.LBB0_226:
	s_or_b64 exec, exec, s[22:23]
	v_cvt_pk_bf16_f32 v102, v88, v89
	v_mul_f32_e32 v89, v89, v89
	v_fmac_f32_e32 v89, v88, v88
	v_mul_f32_e32 v88, v91, v91
	v_fmac_f32_e32 v88, v90, v90
	v_cvt_pk_bf16_f32 v103, v90, v91
	v_add_f32_e32 v88, v89, v88
	v_mul_f32_e32 v89, v97, v97
	v_mul_f32_e32 v90, v99, v99
	v_fmac_f32_e32 v89, v96, v96
	v_fmac_f32_e32 v90, v98, v98
	v_add_f32_e32 v89, v89, v90
	v_add_f32_e32 v88, v89, v88
	v_mul_f32_e32 v89, v85, v85
	v_mul_f32_e32 v90, v87, v87
	v_fmac_f32_e32 v89, v84, v84
	v_fmac_f32_e32 v90, v86, v86
	v_add_f32_e32 v89, v89, v90
	v_mul_f32_e32 v90, v93, v93
	v_mul_f32_e32 v91, v95, v95
	v_fmac_f32_e32 v90, v92, v92
	v_fmac_f32_e32 v91, v94, v94
	v_add_f32_e32 v90, v90, v91
	v_add_f32_e32 v89, v90, v89
	v_add_f32_e32 v90, v89, v88
	v_or_b32_e32 v100, 32, v144
	v_mov_b32_e32 v91, v90
	s_nop 1
	v_permlane16_swap_b32_e32 v91, v90
	s_waitcnt lgkmcnt(0)
	v_ashrrev_i32_e32 v101, 31, v100
	v_readlane_b32 s22, v251, 34
	v_lshlrev_b64 v[106:107], 11, v[100:101]
	v_readlane_b32 s23, v251, 35
	v_cvt_pk_bf16_f32 v104, v96, v97
	v_cvt_pk_bf16_f32 v105, v98, v99
	s_nop 1
	v_lshl_add_u64 v[88:89], s[22:23], 0, v[106:107]
	v_lshl_add_u64 v[96:97], v[142:143], 1, v[88:89]
	global_store_dwordx4 v[96:97], v[102:105], off
	v_cvt_pk_bf16_f32 v88, v84, v85
	v_add_f32_e32 v84, v90, v91
	v_mov_b32_e32 v85, v84
	s_nop 1
	v_permlane32_swap_b32_e32 v85, v84
	v_cvt_pk_bf16_f32 v89, v86, v87
	v_cvt_pk_bf16_f32 v90, v92, v93
	v_cvt_pk_bf16_f32 v91, v94, v95
	global_store_dwordx4 v[96:97], v[88:91], off offset:256
	s_and_saveexec_b64 s[22:23], s[38:39]
	s_cbranch_execz .LBB0_228
	v_readlane_b32 s46, v254, 60
	v_lshlrev_b64 v[86:87], 6, v[100:101]
	v_readlane_b32 s47, v254, 61
	s_lshl_b32 s48, s25, 2
	s_waitcnt lgkmcnt(0)
	v_add_f32_e32 v84, v84, v85
	v_lshl_add_u64 v[86:87], s[46:47], 0, v[86:87]
	v_readlane_b32 s46, v254, 4
	v_readlane_b32 s47, v254, 5
	v_lshl_add_u64 v[86:87], s[20:21], 2, v[86:87]
	s_mov_b32 s49, s47
	v_writelane_b32 v254, s46, 4
	v_lshl_add_u64 v[86:87], v[86:87], 0, s[48:49]
	global_store_dword v[86:87], v84, off
	v_writelane_b32 v254, s47, 5
.LBB0_228:
	s_or_b64 exec, exec, s[22:23]
	v_cvt_pk_bf16_f32 v86, v72, v73
	v_mul_f32_e32 v73, v73, v73
	v_fmac_f32_e32 v73, v72, v72
	v_mul_f32_e32 v72, v75, v75
	v_fmac_f32_e32 v72, v74, v74
	v_cvt_pk_bf16_f32 v87, v74, v75
	v_add_f32_e32 v72, v73, v72
	v_mul_f32_e32 v73, v81, v81
	v_mul_f32_e32 v74, v83, v83
	v_fmac_f32_e32 v73, v80, v80
	v_fmac_f32_e32 v74, v82, v82
	v_add_f32_e32 v73, v73, v74
	v_add_f32_e32 v72, v73, v72
	v_mul_f32_e32 v73, v69, v69
	v_mul_f32_e32 v74, v71, v71
	v_fmac_f32_e32 v73, v68, v68
	v_fmac_f32_e32 v74, v70, v70
	v_add_f32_e32 v73, v73, v74
	v_mul_f32_e32 v74, v77, v77
	v_mul_f32_e32 v75, v79, v79
	v_fmac_f32_e32 v74, v76, v76
	v_fmac_f32_e32 v75, v78, v78
	v_add_f32_e32 v74, v74, v75
	v_add_f32_e32 v73, v74, v73
	v_add_f32_e32 v74, v73, v72
	v_or_b32_e32 v84, 48, v144
	v_mov_b32_e32 v75, v74
	s_nop 1
	v_permlane16_swap_b32_e32 v75, v74
	s_waitcnt lgkmcnt(0)
	v_ashrrev_i32_e32 v85, 31, v84
	v_readlane_b32 s22, v251, 34
	v_lshlrev_b64 v[90:91], 11, v[84:85]
	v_readlane_b32 s23, v251, 35
	v_cvt_pk_bf16_f32 v88, v80, v81
	v_cvt_pk_bf16_f32 v89, v82, v83
	s_nop 1
	v_lshl_add_u64 v[72:73], s[22:23], 0, v[90:91]
	v_lshl_add_u64 v[80:81], v[142:143], 1, v[72:73]
	global_store_dwordx4 v[80:81], v[86:89], off
	v_cvt_pk_bf16_f32 v72, v68, v69
	v_add_f32_e32 v68, v74, v75
	v_mov_b32_e32 v69, v68
	s_nop 1
	v_permlane32_swap_b32_e32 v69, v68
	v_cvt_pk_bf16_f32 v73, v70, v71
	v_cvt_pk_bf16_f32 v74, v76, v77
	v_cvt_pk_bf16_f32 v75, v78, v79
	global_store_dwordx4 v[80:81], v[72:75], off offset:256
	s_and_saveexec_b64 s[22:23], s[38:39]
	s_cbranch_execz .LBB0_230
	v_readlane_b32 s46, v254, 60
	v_lshlrev_b64 v[70:71], 6, v[84:85]
	v_readlane_b32 s47, v254, 61
	s_lshl_b32 s48, s25, 2
	s_waitcnt lgkmcnt(0)
	v_add_f32_e32 v68, v68, v69
	v_lshl_add_u64 v[70:71], s[46:47], 0, v[70:71]
	v_readlane_b32 s46, v254, 4
	v_readlane_b32 s47, v254, 5
	v_lshl_add_u64 v[70:71], s[20:21], 2, v[70:71]
	s_mov_b32 s49, s47
	v_writelane_b32 v254, s46, 4
	v_lshl_add_u64 v[70:71], v[70:71], 0, s[48:49]
	global_store_dword v[70:71], v68, off
	v_writelane_b32 v254, s47, 5
.LBB0_230:
	s_or_b64 exec, exec, s[22:23]
	v_cvt_pk_bf16_f32 v70, v56, v57
	v_mul_f32_e32 v57, v57, v57
	v_fmac_f32_e32 v57, v56, v56
	v_mul_f32_e32 v56, v59, v59
	v_fmac_f32_e32 v56, v58, v58
	v_cvt_pk_bf16_f32 v71, v58, v59
	v_add_f32_e32 v56, v57, v56
	v_mul_f32_e32 v57, v65, v65
	v_mul_f32_e32 v58, v67, v67
	v_fmac_f32_e32 v57, v64, v64
	v_fmac_f32_e32 v58, v66, v66
	v_add_f32_e32 v57, v57, v58
	v_add_f32_e32 v56, v57, v56
	v_mul_f32_e32 v57, v53, v53
	v_mul_f32_e32 v58, v55, v55
	v_fmac_f32_e32 v57, v52, v52
	v_fmac_f32_e32 v58, v54, v54
	v_add_f32_e32 v57, v57, v58
	v_mul_f32_e32 v58, v61, v61
	v_mul_f32_e32 v59, v63, v63
	v_fmac_f32_e32 v58, v60, v60
	v_fmac_f32_e32 v59, v62, v62
	v_add_f32_e32 v58, v58, v59
	v_add_f32_e32 v57, v58, v57
	v_add_f32_e32 v58, v57, v56
	v_add_u32_e32 v68, 0x80, v144
	v_mov_b32_e32 v59, v58
	s_nop 1
	v_permlane16_swap_b32_e32 v59, v58
	s_waitcnt lgkmcnt(0)
	v_ashrrev_i32_e32 v69, 31, v68
	v_readlane_b32 s22, v251, 34
	v_lshlrev_b64 v[74:75], 11, v[68:69]
	v_readlane_b32 s23, v251, 35
	v_cvt_pk_bf16_f32 v72, v64, v65
	v_cvt_pk_bf16_f32 v73, v66, v67
	s_nop 1
	v_lshl_add_u64 v[56:57], s[22:23], 0, v[74:75]
	v_lshl_add_u64 v[64:65], v[142:143], 1, v[56:57]
	global_store_dwordx4 v[64:65], v[70:73], off
	v_cvt_pk_bf16_f32 v56, v52, v53
	v_add_f32_e32 v52, v58, v59
	v_mov_b32_e32 v53, v52
	s_nop 1
	v_permlane32_swap_b32_e32 v53, v52
	v_cvt_pk_bf16_f32 v57, v54, v55
	v_cvt_pk_bf16_f32 v58, v60, v61
	v_cvt_pk_bf16_f32 v59, v62, v63
	global_store_dwordx4 v[64:65], v[56:59], off offset:256
	s_and_saveexec_b64 s[22:23], s[38:39]
	s_cbranch_execz .LBB0_232
	v_readlane_b32 s46, v254, 60
	v_lshlrev_b64 v[54:55], 6, v[68:69]
	v_readlane_b32 s47, v254, 61
	s_lshl_b32 s48, s25, 2
	s_waitcnt lgkmcnt(0)
	v_add_f32_e32 v52, v52, v53
	v_lshl_add_u64 v[54:55], s[46:47], 0, v[54:55]
	v_readlane_b32 s46, v254, 4
	v_readlane_b32 s47, v254, 5
	v_lshl_add_u64 v[54:55], s[20:21], 2, v[54:55]
	s_mov_b32 s49, s47
	v_writelane_b32 v254, s46, 4
	v_lshl_add_u64 v[54:55], v[54:55], 0, s[48:49]
	global_store_dword v[54:55], v52, off
	v_writelane_b32 v254, s47, 5
.LBB0_232:
	s_or_b64 exec, exec, s[22:23]
	v_cvt_pk_bf16_f32 v54, v40, v41
	v_mul_f32_e32 v41, v41, v41
	v_fmac_f32_e32 v41, v40, v40
	v_mul_f32_e32 v40, v43, v43
	v_fmac_f32_e32 v40, v42, v42
	v_cvt_pk_bf16_f32 v55, v42, v43
	v_add_f32_e32 v40, v41, v40
	v_mul_f32_e32 v41, v49, v49
	v_mul_f32_e32 v42, v51, v51
	v_fmac_f32_e32 v41, v48, v48
	v_fmac_f32_e32 v42, v50, v50
	v_add_f32_e32 v41, v41, v42
	v_add_f32_e32 v40, v41, v40
	v_mul_f32_e32 v41, v37, v37
	v_mul_f32_e32 v42, v39, v39
	v_fmac_f32_e32 v41, v36, v36
	v_fmac_f32_e32 v42, v38, v38
	v_add_f32_e32 v41, v41, v42
	v_mul_f32_e32 v42, v45, v45
	v_mul_f32_e32 v43, v47, v47
	v_fmac_f32_e32 v42, v44, v44
	v_fmac_f32_e32 v43, v46, v46
	v_add_f32_e32 v42, v42, v43
	v_add_f32_e32 v41, v42, v41
	v_add_f32_e32 v42, v41, v40
	v_add_u32_e32 v52, 0x90, v144
	v_mov_b32_e32 v43, v42
	s_nop 1
	v_permlane16_swap_b32_e32 v43, v42
	s_waitcnt lgkmcnt(0)
	v_ashrrev_i32_e32 v53, 31, v52
	v_readlane_b32 s22, v251, 34
	v_lshlrev_b64 v[58:59], 11, v[52:53]
	v_readlane_b32 s23, v251, 35
	v_cvt_pk_bf16_f32 v56, v48, v49
	v_cvt_pk_bf16_f32 v57, v50, v51
	s_nop 1
	v_lshl_add_u64 v[40:41], s[22:23], 0, v[58:59]
	v_lshl_add_u64 v[48:49], v[142:143], 1, v[40:41]
	global_store_dwordx4 v[48:49], v[54:57], off
	v_cvt_pk_bf16_f32 v40, v36, v37
	v_add_f32_e32 v36, v42, v43
	v_mov_b32_e32 v37, v36
	s_nop 1
	v_permlane32_swap_b32_e32 v37, v36
	v_cvt_pk_bf16_f32 v41, v38, v39
	v_cvt_pk_bf16_f32 v42, v44, v45
	v_cvt_pk_bf16_f32 v43, v46, v47
	global_store_dwordx4 v[48:49], v[40:43], off offset:256
	s_and_saveexec_b64 s[22:23], s[38:39]
	s_cbranch_execz .LBB0_234
	v_readlane_b32 s46, v254, 60
	v_lshlrev_b64 v[38:39], 6, v[52:53]
	v_readlane_b32 s47, v254, 61
	s_lshl_b32 s48, s25, 2
	s_waitcnt lgkmcnt(0)
	v_add_f32_e32 v36, v36, v37
	v_lshl_add_u64 v[38:39], s[46:47], 0, v[38:39]
	v_readlane_b32 s46, v254, 4
	v_readlane_b32 s47, v254, 5
	v_lshl_add_u64 v[38:39], s[20:21], 2, v[38:39]
	s_mov_b32 s49, s47
	v_writelane_b32 v254, s46, 4
	v_lshl_add_u64 v[38:39], v[38:39], 0, s[48:49]
	global_store_dword v[38:39], v36, off
	v_writelane_b32 v254, s47, 5
.LBB0_234:
	s_or_b64 exec, exec, s[22:23]
	v_cvt_pk_bf16_f32 v38, v24, v25
	v_mul_f32_e32 v25, v25, v25
	v_fmac_f32_e32 v25, v24, v24
	v_mul_f32_e32 v24, v27, v27
	v_fmac_f32_e32 v24, v26, v26
	v_cvt_pk_bf16_f32 v39, v26, v27
	v_add_f32_e32 v24, v25, v24
	v_mul_f32_e32 v25, v33, v33
	v_mul_f32_e32 v26, v35, v35
	v_fmac_f32_e32 v25, v32, v32
	v_fmac_f32_e32 v26, v34, v34
	v_add_f32_e32 v25, v25, v26
	v_add_f32_e32 v24, v25, v24
	v_mul_f32_e32 v25, v21, v21
	v_mul_f32_e32 v26, v23, v23
	v_fmac_f32_e32 v25, v20, v20
	v_fmac_f32_e32 v26, v22, v22
	v_add_f32_e32 v25, v25, v26
	v_mul_f32_e32 v26, v29, v29
	v_mul_f32_e32 v27, v31, v31
	v_fmac_f32_e32 v26, v28, v28
	v_fmac_f32_e32 v27, v30, v30
	v_add_f32_e32 v26, v26, v27
	v_add_f32_e32 v25, v26, v25
	v_add_f32_e32 v26, v25, v24
	v_add_u32_e32 v36, 0xa0, v144
	v_mov_b32_e32 v27, v26
	s_nop 1
	v_permlane16_swap_b32_e32 v27, v26
	s_waitcnt lgkmcnt(0)
	v_ashrrev_i32_e32 v37, 31, v36
	v_readlane_b32 s22, v251, 34
	v_lshlrev_b64 v[42:43], 11, v[36:37]
	v_readlane_b32 s23, v251, 35
	v_cvt_pk_bf16_f32 v40, v32, v33
	v_cvt_pk_bf16_f32 v41, v34, v35
	s_nop 1
	v_lshl_add_u64 v[24:25], s[22:23], 0, v[42:43]
	v_lshl_add_u64 v[32:33], v[142:143], 1, v[24:25]
	global_store_dwordx4 v[32:33], v[38:41], off
	v_cvt_pk_bf16_f32 v24, v20, v21
	v_add_f32_e32 v20, v26, v27
	v_mov_b32_e32 v21, v20
	s_nop 1
	v_permlane32_swap_b32_e32 v21, v20
	v_cvt_pk_bf16_f32 v25, v22, v23
	v_cvt_pk_bf16_f32 v26, v28, v29
	v_cvt_pk_bf16_f32 v27, v30, v31
	global_store_dwordx4 v[32:33], v[24:27], off offset:256
	s_and_saveexec_b64 s[22:23], s[38:39]
	s_cbranch_execz .LBB0_236
	v_readlane_b32 s46, v254, 60
	v_lshlrev_b64 v[22:23], 6, v[36:37]
	v_readlane_b32 s47, v254, 61
	s_lshl_b32 s48, s25, 2
	s_waitcnt lgkmcnt(0)
	v_add_f32_e32 v20, v20, v21
	v_lshl_add_u64 v[22:23], s[46:47], 0, v[22:23]
	v_readlane_b32 s46, v254, 4
	v_readlane_b32 s47, v254, 5
	v_lshl_add_u64 v[22:23], s[20:21], 2, v[22:23]
	s_mov_b32 s49, s47
	v_writelane_b32 v254, s46, 4
	v_lshl_add_u64 v[22:23], v[22:23], 0, s[48:49]
	global_store_dword v[22:23], v20, off
	v_writelane_b32 v254, s47, 5
.LBB0_236:
	s_or_b64 exec, exec, s[22:23]
	v_cvt_pk_bf16_f32 v22, v8, v9
	v_mul_f32_e32 v9, v9, v9
	v_fmac_f32_e32 v9, v8, v8
	v_mul_f32_e32 v8, v11, v11
	v_fmac_f32_e32 v8, v10, v10
	v_cvt_pk_bf16_f32 v23, v10, v11
	v_add_f32_e32 v8, v9, v8
	v_mul_f32_e32 v9, v17, v17
	v_mul_f32_e32 v10, v19, v19
	v_fmac_f32_e32 v9, v16, v16
	v_fmac_f32_e32 v10, v18, v18
	v_add_f32_e32 v9, v9, v10
	v_add_f32_e32 v8, v9, v8
	v_mul_f32_e32 v9, v5, v5
	v_mul_f32_e32 v10, v7, v7
	v_fmac_f32_e32 v9, v4, v4
	v_fmac_f32_e32 v10, v6, v6
	v_add_f32_e32 v9, v9, v10
	v_mul_f32_e32 v10, v13, v13
	v_mul_f32_e32 v11, v15, v15
	v_fmac_f32_e32 v10, v12, v12
	v_fmac_f32_e32 v11, v14, v14
	v_add_f32_e32 v10, v10, v11
	v_add_f32_e32 v9, v10, v9
	v_add_f32_e32 v10, v9, v8
	v_add_u32_e32 v20, 0xb0, v144
	v_mov_b32_e32 v11, v10
	s_nop 1
	v_permlane16_swap_b32_e32 v11, v10
	s_waitcnt lgkmcnt(0)
	v_ashrrev_i32_e32 v21, 31, v20
	v_readlane_b32 s22, v251, 34
	v_lshlrev_b64 v[26:27], 11, v[20:21]
	v_readlane_b32 s23, v251, 35
	v_cvt_pk_bf16_f32 v24, v16, v17
	v_cvt_pk_bf16_f32 v25, v18, v19
	s_nop 1
	v_lshl_add_u64 v[8:9], s[22:23], 0, v[26:27]
	v_lshl_add_u64 v[16:17], v[142:143], 1, v[8:9]
	global_store_dwordx4 v[16:17], v[22:25], off
	v_cvt_pk_bf16_f32 v8, v4, v5
	v_add_f32_e32 v4, v10, v11
	v_mov_b32_e32 v5, v4
	s_nop 1
	v_permlane32_swap_b32_e32 v5, v4
	v_cvt_pk_bf16_f32 v9, v6, v7
	v_cvt_pk_bf16_f32 v10, v12, v13
	v_cvt_pk_bf16_f32 v11, v14, v15
	global_store_dwordx4 v[16:17], v[8:11], off offset:256
	s_and_saveexec_b64 s[22:23], s[38:39]
	s_cbranch_execz .LBB0_238
	v_readlane_b32 s46, v254, 60
	v_lshlrev_b64 v[6:7], 6, v[20:21]
	v_readlane_b32 s47, v254, 61
	s_waitcnt lgkmcnt(0)
	v_add_f32_e32 v4, v4, v5
	v_lshl_add_u64 v[6:7], s[46:47], 0, v[6:7]
	v_lshl_add_u64 v[6:7], s[20:21], 2, v[6:7]
	v_readlane_b32 s20, v254, 4
	v_readlane_b32 s21, v254, 5
	s_mov_b32 s47, s21
	s_lshl_b32 s46, s25, 2
	v_writelane_b32 v254, s20, 4
	v_lshl_add_u64 v[6:7], v[6:7], 0, s[46:47]
	global_store_dword v[6:7], v4, off
	v_writelane_b32 v254, s21, 5

; __device__ __forceinline__ void co_phase(Frame& F, int layer, const float* cwa_, const float* cba_, const float* lng_, const float* lnb_, const float* cwb_, const float* p_) {
;     ...
;             for (int s = 0; s < CO_R + CKA - 1; ++s) { const int gr = (t0 - (CKA - 1) + s >= 0) ? g0 - (CKA - 1) + s : g0; in[s] = AGLU[(size_t)gr * (DC / 2) + (c0 >> 1)]; }
;             if (t0 < CKA - 1) CoStep<0, true>::run(acc, w, in, t0); else CoStep<0, false>::run(acc, w, in, t0);
;         }
;         {
;             float vals[2 * CO_R];
; #pragma unroll
;             for (int r = 0; r < CO_R; ++r) { vals[r] = acc[r].x + acc[r].y; vals[CO_R + r] = acc[r].x * acc[r].x + acc[r].y * acc[r].y; }
; #pragma unroll
;             for (int half = CO_R, bit = 32; half >= 1; half >>= 1, bit >>= 1) {
;                 const bool up = (F.lane & bit) != 0;
; #pragma unroll
;                 for (int i = 0; i < half; ++i) { const float send = up ? vals[i] : vals[i + half], keep = up ? vals[i + half] : vals[i]; vals[i] = keep + __shfl_xor(send, bit, 64); }
.LBB0_285:
	v_lshl_add_u64 v[164:165], v[82:83], 0, s[20:21]
	global_load_dword v130, v[164:165], off
	v_lshl_add_u64 v[164:165], v[82:83], 0, s[82:83]
	global_load_dword v131, v[164:165], off
	v_lshl_add_u64 v[164:165], v[82:83], 0, s[84:85]
	global_load_dword v132, v[164:165], off
	v_lshl_add_u64 v[164:165], v[82:83], 0, s[86:87]
	global_load_dword v133, v[164:165], off
	v_lshl_add_u64 v[164:165], v[82:83], 0, s[90:91]
	global_load_dword v134, v[164:165], off
	v_lshl_add_u64 v[164:165], v[82:83], 0, s[48:49]
	global_load_dword v135, v[164:165], off
	v_lshl_add_u64 v[164:165], v[82:83], 0, s[46:47]
	global_load_dword v136, v[164:165], off
	v_lshl_add_u64 v[164:165], v[82:83], 0, s[24:25]
	global_load_dword v137, v[164:165], off
	v_lshl_add_u64 v[164:165], v[82:83], 0, s[88:89]
	global_load_dword v138, v[164:165], off
	v_lshl_add_u64 v[164:165], v[82:83], 0, s[4:5]
	global_load_dword v139, v[164:165], off
	v_lshl_add_u64 v[164:165], v[82:83], 0, s[16:17]
	global_load_dword v140, v[164:165], off
	v_lshl_add_u64 v[164:165], v[82:83], 0, s[30:31]
	global_load_dword v141, v[164:165], off
	v_lshl_add_u64 v[164:165], v[82:83], 0, s[18:19]
	global_load_dword v142, v[164:165], off
	v_lshl_add_u64 v[164:165], v[82:83], 0, s[28:29]
	global_load_dword v143, v[164:165], off
	v_lshl_add_u64 v[164:165], v[82:83], 0, s[26:27]
	global_load_dword v144, v[164:165], off
	v_lshl_add_u64 v[164:165], v[82:83], 0, s[8:9]
	global_load_dword v145, v[164:165], off
	v_lshl_add_u64 v[164:165], v[84:85], 0, s[20:21]
	global_load_dword v146, v[164:165], off
	s_mov_b32 s98, s60
	s_ashr_i32 s99, s60, 31
	s_lshl_b64 s[98:99], s[98:99], 10
	v_lshl_add_u64 v[164:165], v[84:85], 0, s[98:99]
	global_load_dword v147, v[164:165], off
	s_mov_b32 s98, s6
	s_ashr_i32 s99, s6, 31
	s_lshl_b64 s[98:99], s[98:99], 10
	v_lshl_add_u64 v[164:165], v[84:85], 0, s[98:99]
	global_load_dword v148, v[164:165], off
	s_mov_b32 s98, s76
	s_ashr_i32 s99, s76, 31
	s_lshl_b64 s[98:99], s[98:99], 10
	v_lshl_add_u64 v[164:165], v[84:85], 0, s[98:99]
	global_load_dword v149, v[164:165], off
	s_mov_b32 s98, s36
	s_ashr_i32 s99, s36, 31
	s_lshl_b64 s[98:99], s[98:99], 10
	v_lshl_add_u64 v[164:165], v[84:85], 0, s[98:99]
	global_load_dword v150, v[164:165], off
	s_mov_b32 s98, s22
	s_ashr_i32 s99, s22, 31
	s_lshl_b64 s[98:99], s[98:99], 10
	v_lshl_add_u64 v[164:165], v[84:85], 0, s[98:99]
	global_load_dword v151, v[164:165], off
	s_mov_b32 s98, s78
	s_ashr_i32 s99, s78, 31
	s_lshl_b64 s[98:99], s[98:99], 10
	v_lshl_add_u64 v[164:165], v[84:85], 0, s[98:99]
	global_load_dword v152, v[164:165], off
	s_mov_b32 s98, s80
	s_ashr_i32 s99, s80, 31
	s_lshl_b64 s[98:99], s[98:99], 10
	v_lshl_add_u64 v[164:165], v[84:85], 0, s[98:99]
	global_load_dword v153, v[164:165], off
	s_mov_b32 s98, s34
	s_ashr_i32 s99, s34, 31
	s_lshl_b64 s[98:99], s[98:99], 10
	v_lshl_add_u64 v[164:165], v[84:85], 0, s[98:99]
	global_load_dword v154, v[164:165], off
	s_mov_b32 s98, s52
	s_ashr_i32 s99, s52, 31
	s_lshl_b64 s[98:99], s[98:99], 10
	v_lshl_add_u64 v[164:165], v[84:85], 0, s[98:99]
	global_load_dword v155, v[164:165], off
	s_mov_b32 s98, s54
	s_ashr_i32 s99, s54, 31
	s_lshl_b64 s[98:99], s[98:99], 10
	v_lshl_add_u64 v[164:165], v[84:85], 0, s[98:99]
	global_load_dword v156, v[164:165], off
	s_mov_b32 s98, s92
	s_ashr_i32 s99, s92, 31
	s_lshl_b64 s[98:99], s[98:99], 10
	v_lshl_add_u64 v[164:165], v[84:85], 0, s[98:99]
	global_load_dword v157, v[164:165], off
	s_mov_b32 s98, s96
	s_ashr_i32 s99, s96, 31
	s_lshl_b64 s[98:99], s[98:99], 10
	v_lshl_add_u64 v[164:165], v[84:85], 0, s[98:99]
	global_load_dword v158, v[164:165], off
	s_mov_b32 s98, s58
	s_ashr_i32 s99, s58, 31
	s_lshl_b64 s[98:99], s[98:99], 10
	v_lshl_add_u64 v[164:165], v[84:85], 0, s[98:99]
	global_load_dword v159, v[164:165], off
	s_mov_b32 s98, s56
	s_ashr_i32 s99, s56, 31
	s_lshl_b64 s[98:99], s[98:99], 10
	v_lshl_add_u64 v[164:165], v[84:85], 0, s[98:99]
	global_load_dword v162, v[164:165], off
	s_mov_b32 s98, s12
	s_ashr_i32 s99, s12, 31
	s_lshl_b64 s[98:99], s[98:99], 10
	v_lshl_add_u64 v[164:165], v[84:85], 0, s[98:99]
	global_load_dword v163, v[164:165], off
	v_mul_f32_e32 v97, v183, v183
	v_mul_f32_e32 v99, v187, v187
	v_add_f32_e32 v96, v182, v183
	v_fmac_f32_e32 v97, v182, v182
	v_add_f32_e32 v98, v186, v187
	v_fmac_f32_e32 v99, v186, v186
	v_mul_f32_e32 v101, v191, v191
	v_add_f32_e32 v100, v190, v191
	v_fmac_f32_e32 v101, v190, v190
	v_mul_f32_e32 v105, v189, v189
	v_mul_f32_e32 v103, v193, v193
	v_add_f32_e32 v104, v188, v189
	v_fmac_f32_e32 v105, v188, v188
	v_mul_f32_e32 v107, v185, v185
	v_add_f32_e32 v102, v192, v193
	v_fmac_f32_e32 v103, v192, v192
	v_add_f32_e32 v106, v184, v185
	v_fmac_f32_e32 v107, v184, v184
	v_mul_f32_e32 v109, v181, v181
	v_add_f32_e32 v108, v180, v181
	v_fmac_f32_e32 v109, v180, v180
	v_mul_f32_e32 v111, v179, v179
	v_add_f32_e32 v110, v178, v179
	v_fmac_f32_e32 v111, v178, v178
	v_mul_f32_e32 v113, v177, v177
	v_add_f32_e32 v112, v176, v177
	v_fmac_f32_e32 v113, v176, v176
	v_mul_f32_e32 v115, v175, v175
	v_add_f32_e32 v114, v174, v175
	v_fmac_f32_e32 v115, v174, v174
	v_mul_f32_e32 v117, v173, v173
	v_add_f32_e32 v116, v172, v173
	v_fmac_f32_e32 v117, v172, v172
	v_mul_f32_e32 v119, v171, v171
	v_add_f32_e32 v118, v170, v171
	v_fmac_f32_e32 v119, v170, v170
	v_mul_f32_e32 v121, v169, v169
	v_add_f32_e32 v120, v168, v169
	v_fmac_f32_e32 v121, v168, v168
	v_mul_f32_e32 v123, v167, v167
	v_pk_fma_f32 v[94:95], v[66:67], v[202:203], v[200:201]
	v_add_f32_e32 v122, v166, v167
	v_fmac_f32_e32 v123, v166, v166
	v_mul_f32_e32 v125, v161, v161
	v_add_f32_e32 v124, v160, v161
	v_fmac_f32_e32 v125, v160, v160
	v_mul_f32_e32 v128, v94, v94
	v_add_f32_e32 v127, v95, v94
	v_fmac_f32_e32 v128, v95, v95
	s_waitcnt lgkmcnt(0)
; #define LAS __attribute__((address_space(3)))
; __device__ __forceinline__ void co_phase(Frame& F, int layer, const float* cwa_, const float* cba_, const float* lng_, const float* lnb_, const float* cwb_, const float* p_) {
;     ...
; #pragma unroll
;             for (int half = CO_R, bit = 32; half >= 1; half >>= 1, bit >>= 1) {
;                 const bool up = (F.lane & bit) != 0;
; #pragma unroll
;                 for (int i = 0; i < half; ++i) { const float send = up ? vals[i] : vals[i + half], keep = up ? vals[i + half] : vals[i]; vals[i] = keep + __shfl_xor(send, bit, 64); }
;             }
;             static_assert(CO_R == 16 || CO_R == 32, "the butterfly below ends with 2 (CO_R = 16) or 1 (CO_R = 32) lanes per value");
;             const float tot = CO_R == 16 ? vals[0] + __shfl_xor(vals[0], 1, 64) : vals[0];
;             const int idx = CO_R == 16 ? ((F.lane >> 1) & 31) : F.lane;
;             if (CO_R == 32 || (F.lane & 1) == 0) ((LAS float*)part)[((idx & (CO_R - 1)) * 4 + wv) * 2 + (idx >= CO_R ? 1 : 0)] = tot;
	s_nop 1
	v_permlane32_swap_b32_e32 v96, v97
	v_add_f32_e32 v96, v96, v97
	v_permlane32_swap_b32_e32 v98, v99
	v_add_f32_e32 v97, v98, v99
	v_permlane32_swap_b32_e32 v100, v101
	v_add_f32_e32 v98, v100, v101
	v_permlane32_swap_b32_e32 v104, v105
	v_add_f32_e32 v100, v104, v105
	v_permlane32_swap_b32_e32 v102, v103
	v_add_f32_e32 v99, v102, v103
	v_permlane32_swap_b32_e32 v106, v107
	v_add_f32_e32 v101, v106, v107
	v_permlane32_swap_b32_e32 v108, v109
	v_add_f32_e32 v102, v108, v109
	v_permlane32_swap_b32_e32 v110, v111
	v_add_f32_e32 v103, v110, v111
	v_permlane32_swap_b32_e32 v112, v113
	v_add_f32_e32 v104, v112, v113
	v_permlane32_swap_b32_e32 v114, v115
	v_add_f32_e32 v105, v114, v115
	v_permlane32_swap_b32_e32 v116, v117
	v_add_f32_e32 v106, v116, v117
	v_permlane32_swap_b32_e32 v118, v119
	v_add_f32_e32 v107, v118, v119
	v_permlane32_swap_b32_e32 v120, v121
	v_add_f32_e32 v108, v120, v121
	v_permlane32_swap_b32_e32 v122, v123
	v_add_f32_e32 v109, v122, v123
	v_permlane32_swap_b32_e32 v124, v125
	v_add_f32_e32 v110, v124, v125
	v_permlane32_swap_b32_e32 v127, v128
	v_add_f32_e32 v111, v127, v128
	s_nop 1
	v_permlane16_swap_b32_e32 v96, v104
	v_add_f32_e32 v96, v96, v104
	v_permlane16_swap_b32_e32 v97, v105
	v_add_f32_e32 v97, v97, v105
	v_permlane16_swap_b32_e32 v100, v108
	v_add_f32_e32 v100, v100, v108
	v_permlane16_swap_b32_e32 v99, v107
	v_add_f32_e32 v99, v99, v107
	v_permlane16_swap_b32_e32 v98, v106
	v_add_f32_e32 v98, v98, v106
	v_permlane16_swap_b32_e32 v101, v109
	v_add_f32_e32 v101, v101, v109
	v_permlane16_swap_b32_e32 v102, v110
	v_add_f32_e32 v102, v102, v110
	v_permlane16_swap_b32_e32 v103, v111
	v_add_f32_e32 v103, v103, v111
	v_cndmask_b32_e64 v106, v96, v100, s[42:43]
	v_cndmask_b32_e64 v96, v100, v96, s[42:43]
	v_cndmask_b32_e64 v100, v97, v101, s[42:43]
	v_cndmask_b32_e64 v97, v101, v97, s[42:43]
	v_cndmask_b32_e64 v101, v98, v102, s[42:43]
	v_cndmask_b32_e64 v104, v99, v103, s[42:43]
	ds_bpermute_b32 v106, v206, v106
	ds_bpermute_b32 v100, v206, v100
	ds_bpermute_b32 v101, v206, v101
	ds_bpermute_b32 v104, v206, v104
	v_cndmask_b32_e64 v98, v102, v98, s[42:43]
	v_cndmask_b32_e64 v99, v103, v99, s[42:43]
	s_waitcnt lgkmcnt(3)
	v_add_f32_e32 v96, v96, v106
	s_waitcnt lgkmcnt(2)
	v_add_f32_e32 v97, v97, v100
	s_waitcnt lgkmcnt(1)
	v_add_f32_e32 v98, v98, v101
	s_waitcnt lgkmcnt(0)
	v_add_f32_e32 v99, v99, v104
	v_cndmask_b32_e64 v100, v96, v98, s[44:45]
	v_cndmask_b32_e64 v101, v97, v99, s[44:45]
	ds_bpermute_b32 v100, v207, v100
	ds_bpermute_b32 v101, v207, v101
	v_cndmask_b32_e64 v96, v98, v96, s[44:45]
	v_cndmask_b32_e64 v97, v99, v97, s[44:45]
	s_waitcnt lgkmcnt(1)
	v_add_f32_e32 v96, v96, v100
	s_waitcnt lgkmcnt(0)
	v_add_f32_e32 v97, v97, v101
	v_cndmask_b32_e64 v98, v96, v97, s[62:63]
	ds_bpermute_b32 v98, v208, v98
	v_cndmask_b32_e64 v96, v97, v96, s[62:63]
	s_waitcnt lgkmcnt(0)
	v_add_f32_e32 v96, v96, v98
	ds_bpermute_b32 v97, v204, v96
	s_and_saveexec_b64 s[50:51], s[64:65]
	s_cbranch_execz .LBB0_287
	s_waitcnt lgkmcnt(0)
	v_add_f32_e32 v96, v96, v97
	ds_write_b32 v209, v96

.LBB0_434:
	v_lshl_add_u32 v192, s13, 8, v220
	v_ashrrev_i32_e32 v193, 31, v192
	v_lshlrev_b64 v[200:201], 6, v[192:193]
	v_lshl_add_u64 v[132:133], v[170:171], 0, v[200:201]
	global_load_dwordx4 v[132:135], v[132:133], off
	v_or_b32_e32 v190, 16, v192
	v_ashrrev_i32_e32 v191, 31, v190
	v_lshlrev_b64 v[202:203], 6, v[190:191]
	v_lshl_add_u64 v[136:137], v[170:171], 0, v[202:203]
	global_load_dwordx4 v[136:139], v[136:137], off
	v_or_b32_e32 v188, 32, v192
	v_ashrrev_i32_e32 v189, 31, v188
	v_lshlrev_b64 v[204:205], 6, v[188:189]
	v_lshl_add_u64 v[140:141], v[170:171], 0, v[204:205]
	global_load_dwordx4 v[140:143], v[140:141], off
	v_or_b32_e32 v186, 48, v192
	v_ashrrev_i32_e32 v187, 31, v186
	v_lshlrev_b64 v[206:207], 6, v[186:187]
	v_lshl_add_u64 v[144:145], v[170:171], 0, v[206:207]
	global_load_dwordx4 v[144:147], v[144:145], off
	v_add_u32_e32 v184, 0x80, v192
	v_ashrrev_i32_e32 v185, 31, v184
	v_lshlrev_b64 v[208:209], 6, v[184:185]
	v_lshl_add_u64 v[148:149], v[170:171], 0, v[208:209]
	global_load_dwordx4 v[148:151], v[148:149], off
	v_add_u32_e32 v182, 0x90, v192
	v_ashrrev_i32_e32 v183, 31, v182
	v_lshlrev_b64 v[210:211], 6, v[182:183]
	v_lshl_add_u64 v[152:153], v[170:171], 0, v[210:211]
	global_load_dwordx4 v[152:155], v[152:153], off
	v_add_u32_e32 v180, 0xa0, v192
	v_ashrrev_i32_e32 v181, 31, v180
	v_lshlrev_b64 v[212:213], 6, v[180:181]
	v_lshl_add_u64 v[156:157], v[170:171], 0, v[212:213]
	global_load_dwordx4 v[156:159], v[156:157], off
	v_add_u32_e32 v178, 0xb0, v192
	v_ashrrev_i32_e32 v179, 31, v178
	v_lshlrev_b64 v[214:215], 6, v[178:179]
	v_lshl_add_u64 v[160:161], v[170:171], 0, v[214:215]
	global_load_dwordx4 v[160:163], v[160:161], off
	v_xor_b32_e32 v232, 64, v224
	v_xor_b32_e32 v225, 0x80, v224
	v_lshl_or_b32 v198, s12, 8, v222
	v_ashrrev_i32_e32 v199, 31, v198
	v_lshlrev_b64 v[218:219], 11, v[192:193]
	v_lshl_add_u32 v224, v192, 10, v198
	v_lshlrev_b32_e32 v224, 1, v224
	global_load_dwordx4 v[164:167], v224, s[44:45]
	global_load_dwordx4 v[168:171], v224, s[44:45] offset:256
	v_lshl_add_u32 v224, v190, 10, v198
	v_lshlrev_b32_e32 v224, 1, v224
	global_load_dwordx4 v[174:177], v224, s[44:45]
	global_load_dwordx4 v[220:223], v224, s[44:45] offset:256
	s_and_b64 vcc, exec, s[28:29]
	s_waitcnt vmcnt(4)
	v_mov_b32_e32 v216, v133
	v_mov_b32_e32 v217, v134
	v_mov_b32_e32 v133, v135
	v_pk_add_f32 v[132:133], v[216:217], v[132:133]
	s_nop 0
	v_add_f32_e32 v132, v132, v133
	v_mov_b32_e32 v133, v132
	s_nop 1
	v_permlane16_swap_b32_e32 v133, v132
	s_waitcnt lgkmcnt(0)
	v_add_f32_e32 v132, v132, v133
	v_mov_b32_e32 v133, v132
	s_nop 1
	v_permlane32_swap_b32_e32 v133, v132
	s_waitcnt lgkmcnt(0)
	v_add_f32_e32 v132, v132, v133
	v_fmamk_f32 v132, v132, 0x3a800000, v226
	v_rsq_f32_e32 v216, v132
	v_add_f32_e32 v132, v136, v137
	v_add_f32_e32 v133, v138, v139
	v_add_f32_e32 v132, v132, v133
	v_mov_b32_e32 v133, v132
	s_nop 1
	v_permlane16_swap_b32_e32 v133, v132
	v_pk_mul_f32 v[128:129], v[128:129], v[216:217] op_sel_hi:[1,0]
	v_pk_mul_f32 v[130:131], v[130:131], v[216:217] op_sel_hi:[1,0]
	v_pk_mul_f32 v[128:129], v[128:129], s[14:15] op_sel_hi:[1,0]
	v_pk_mul_f32 v[130:131], v[130:131], s[14:15] op_sel_hi:[1,0]
	s_waitcnt lgkmcnt(0)
	v_add_f32_e32 v245, v132, v133
	v_add_f32_e32 v132, v140, v141
	v_add_f32_e32 v133, v142, v143
	v_add_f32_e32 v132, v132, v133
	v_mov_b32_e32 v133, v132
	s_nop 1
	v_permlane16_swap_b32_e32 v133, v132
	v_pk_mul_f32 v[124:125], v[124:125], v[216:217] op_sel_hi:[1,0]
	v_pk_mul_f32 v[126:127], v[126:127], v[216:217] op_sel_hi:[1,0]
	v_exp_f32_e32 v128, v128
	v_exp_f32_e32 v129, v129
	s_waitcnt lgkmcnt(0)
	v_add_f32_e32 v243, v132, v133
	v_add_f32_e32 v132, v144, v145
	v_add_f32_e32 v133, v146, v147
	v_add_f32_e32 v132, v132, v133
	v_mov_b32_e32 v133, v132
	s_nop 1
	v_permlane16_swap_b32_e32 v133, v132
	v_exp_f32_e32 v130, v130
	v_exp_f32_e32 v131, v131
	v_pk_mul_f32 v[126:127], v[126:127], s[14:15] op_sel_hi:[1,0]
	v_pk_mul_f32 v[124:125], v[124:125], s[14:15] op_sel_hi:[1,0]
	s_waitcnt lgkmcnt(0)
	v_add_f32_e32 v241, v132, v133
	v_add_f32_e32 v132, v148, v149
	v_add_f32_e32 v133, v150, v151
	v_add_f32_e32 v132, v132, v133
	v_mov_b32_e32 v133, v132
	s_nop 1
	v_permlane16_swap_b32_e32 v133, v132
	v_exp_f32_e32 v124, v124
	v_exp_f32_e32 v125, v125
	v_exp_f32_e32 v126, v126
	v_exp_f32_e32 v127, v127
	s_waitcnt lgkmcnt(0)
	v_add_f32_e32 v239, v132, v133
	v_add_f32_e32 v132, v152, v153
	v_add_f32_e32 v133, v154, v155
	v_add_f32_e32 v132, v132, v133
	v_mov_b32_e32 v133, v132
	s_nop 1
	v_permlane16_swap_b32_e32 v133, v132
	v_pk_add_f32 v[130:131], v[130:131], 1.0 op_sel_hi:[1,0]
	v_pk_add_f32 v[128:129], v[128:129], 1.0 op_sel_hi:[1,0]
	v_rcp_f32_e32 v130, v130
	v_rcp_f32_e32 v128, v128
	s_waitcnt lgkmcnt(0)
	v_add_f32_e32 v237, v132, v133
	v_add_f32_e32 v132, v156, v157
	v_add_f32_e32 v133, v158, v159
	v_add_f32_e32 v132, v132, v133
	v_mov_b32_e32 v133, v132
	s_nop 1
	v_permlane16_swap_b32_e32 v133, v132
	v_rcp_f32_e32 v129, v129
	v_rcp_f32_e32 v131, v131
	v_pk_add_f32 v[126:127], v[126:127], 1.0 op_sel_hi:[1,0]
	v_pk_add_f32 v[124:125], v[124:125], 1.0 op_sel_hi:[1,0]
	s_waitcnt lgkmcnt(0)
	v_add_f32_e32 v235, v132, v133
	v_add_f32_e32 v132, v160, v161
	v_add_f32_e32 v133, v162, v163
	v_add_f32_e32 v132, v132, v133
	v_mov_b32_e32 v133, v132
	s_nop 1
	v_permlane16_swap_b32_e32 v133, v132
	ds_bpermute_b32 v246, v225, v245
	ds_bpermute_b32 v244, v225, v243
	ds_bpermute_b32 v242, v225, v241
	ds_bpermute_b32 v240, v225, v239
	s_waitcnt lgkmcnt(4)
	v_add_f32_e32 v233, v132, v133
	v_lshlrev_b64 v[132:133], 10, v[192:193]
	v_lshl_add_u64 v[132:133], v[132:133], 0, v[198:199]
	v_lshlrev_b64 v[132:133], 1, v[132:133]
	v_lshl_add_u64 v[134:135], s[42:43], 0, v[132:133]
	global_load_dwordx4 v[156:159], v[134:135], off
	v_or_b32_e32 v132, 0x100, v132
	v_lshl_add_u64 v[134:135], s[42:43], 0, v[132:133]
	global_load_dwordx4 v[148:151], v[134:135], off
	v_lshlrev_b64 v[132:133], 10, v[190:191]
	v_lshl_add_u64 v[132:133], v[132:133], 0, v[198:199]
	v_lshlrev_b64 v[136:137], 1, v[132:133]
	v_lshl_add_u64 v[132:133], s[42:43], 0, v[136:137]
	global_load_dwordx4 v[140:143], v[132:133], off
	v_or_b32_e32 v136, 0x100, v136
	v_lshl_add_u64 v[132:133], s[42:43], 0, v[136:137]
	global_load_dwordx4 v[132:135], v[132:133], off
	ds_bpermute_b32 v238, v225, v237
	ds_bpermute_b32 v236, v225, v235
	s_waitcnt vmcnt(4)
	v_mov_b32_e32 v160, v164
	v_mov_b32_e32 v161, v165
	v_mov_b32_e32 v162, v166
	v_mov_b32_e32 v163, v167
	v_mov_b32_e32 v152, v168
	v_mov_b32_e32 v153, v169
	v_mov_b32_e32 v154, v170
	v_mov_b32_e32 v155, v171
	v_mov_b32_e32 v144, v174
	v_mov_b32_e32 v145, v175
	v_mov_b32_e32 v146, v176
	v_mov_b32_e32 v147, v177
	v_mov_b32_e32 v136, v220
	v_mov_b32_e32 v137, v221
	v_mov_b32_e32 v138, v222
	v_mov_b32_e32 v139, v223
	v_lshl_add_u32 v224, v188, 10, v198
	v_lshlrev_b32_e32 v224, 1, v224
	global_load_dwordx4 v[164:167], v224, s[44:45]
	global_load_dwordx4 v[168:171], v224, s[44:45] offset:256
	v_lshl_add_u32 v224, v186, 10, v198
	v_lshlrev_b32_e32 v224, 1, v224
	global_load_dwordx4 v[174:177], v224, s[44:45]
	global_load_dwordx4 v[220:223], v224, s[44:45] offset:256
	ds_bpermute_b32 v234, v225, v233
	v_rcp_f32_e32 v194, v124
	v_rcp_f32_e32 v195, v125
	v_rcp_f32_e32 v196, v126
	v_rcp_f32_e32 v197, v127
	s_waitcnt vmcnt(7)
	v_lshlrev_b32_e32 v126, 16, v156
	v_and_b32_e32 v127, 0xffff0000, v156
	v_lshlrev_b32_e32 v124, 16, v157
	s_waitcnt vmcnt(7)
	v_lshlrev_b32_e32 v248, 16, v160
	v_and_b32_e32 v249, 0xffff0000, v160
	v_lshlrev_b32_e32 v160, 16, v161
	v_and_b32_e32 v161, 0xffff0000, v161
	v_and_b32_e32 v125, 0xffff0000, v157
	v_lshlrev_b32_e32 v230, 16, v162
	v_and_b32_e32 v231, 0xffff0000, v162
	v_lshlrev_b32_e32 v162, 16, v163
	v_and_b32_e32 v163, 0xffff0000, v163
	v_pk_fma_f32 v[124:125], v[130:131], v[160:161], v[124:125]
	v_pk_fma_f32 v[126:127], v[128:129], v[248:249], v[126:127]
	v_lshlrev_b32_e32 v128, 16, v158
	v_and_b32_e32 v129, 0xffff0000, v158
	v_lshlrev_b32_e32 v130, 16, v159
	v_and_b32_e32 v131, 0xffff0000, v159
	v_lshl_add_u64 v[156:157], s[72:73], 0, v[218:219]
	v_pk_fma_f32 v[128:129], v[194:195], v[230:231], v[128:129]
	v_pk_fma_f32 v[130:131], v[196:197], v[162:163], v[130:131]
	v_lshl_add_u64 v[156:157], v[198:199], 1, v[156:157]
	s_cbranch_vccz .LBB0_436
	v_cvt_pk_bf16_f32 v158, v126, v127
	v_cvt_pk_bf16_f32 v159, v124, v125
	v_cvt_pk_bf16_f32 v160, v128, v129
	v_cvt_pk_bf16_f32 v161, v130, v131
	global_store_dwordx4 v[156:157], v[158:161], off

.LBB0_438:
	s_nop 1
	v_mul_f32_e32 v116, v127, v127
	v_mul_f32_e32 v117, v124, v124
	v_fmac_f32_e32 v116, v126, v126
	v_fmac_f32_e32 v117, v125, v125
	v_add_f32_e32 v116, v116, v117
	v_mul_f32_e32 v117, v128, v128
	v_mul_f32_e32 v118, v130, v130
	v_fmac_f32_e32 v117, v129, v129
	v_fmac_f32_e32 v118, v131, v131
	v_add_f32_e32 v117, v118, v117
	v_add_f32_e32 v116, v117, v116
	v_mul_f32_e32 v117, v153, v153
	v_mul_f32_e32 v118, v148, v148
	v_fmac_f32_e32 v117, v152, v152
	v_fmac_f32_e32 v118, v149, v149
	v_add_f32_e32 v117, v117, v118
	v_mul_f32_e32 v118, v150, v150
	v_mul_f32_e32 v119, v154, v154
	v_fmac_f32_e32 v118, v151, v151
	v_fmac_f32_e32 v119, v155, v155
	v_add_f32_e32 v118, v119, v118
	v_add_f32_e32 v117, v118, v117
	v_add_f32_e32 v116, v116, v117
	v_mov_b32_e32 v117, v116
	s_nop 1
	v_permlane16_swap_b32_e32 v117, v116
	s_lshl_b32 s0, s12, 2
	s_ashr_i32 s1, s0, 31
	s_waitcnt lgkmcnt(0)
	v_add_f32_e32 v116, v116, v117
	v_mov_b32_e32 v117, v116
	s_nop 1
	v_permlane32_swap_b32_e32 v117, v116
	s_and_saveexec_b64 s[4:5], s[38:39]
	s_cbranch_execz .LBB0_440
	v_readlane_b32 s6, v254, 60
	v_readlane_b32 s7, v254, 61
	s_lshl_b32 s8, s79, 2
	s_waitcnt lgkmcnt(0)
	v_add_f32_e32 v116, v116, v117
	v_lshl_add_u64 v[118:119], s[6:7], 0, v[200:201]
	v_readlane_b32 s6, v254, 4
	v_readlane_b32 s7, v254, 5
	v_lshl_add_u64 v[118:119], s[0:1], 2, v[118:119]
	s_mov_b32 s9, s7
	v_writelane_b32 v254, s6, 4
	v_lshl_add_u64 v[118:119], v[118:119], 0, s[8:9]
	global_store_dword v[118:119], v116, off
	v_writelane_b32 v254, s7, 5

.LBB0_444:
	s_nop 1
	v_mul_f32_e32 v100, v145, v145
	v_mul_f32_e32 v101, v140, v140
	v_fmac_f32_e32 v100, v144, v144
	v_fmac_f32_e32 v101, v141, v141
	v_add_f32_e32 v100, v100, v101
	v_mul_f32_e32 v101, v142, v142
	v_mul_f32_e32 v102, v146, v146
	v_fmac_f32_e32 v101, v143, v143
	v_fmac_f32_e32 v102, v147, v147
	v_add_f32_e32 v101, v102, v101
	v_add_f32_e32 v100, v101, v100
	v_mul_f32_e32 v101, v137, v137
	v_mul_f32_e32 v102, v132, v132
	v_fmac_f32_e32 v101, v136, v136
	v_fmac_f32_e32 v102, v133, v133
	v_add_f32_e32 v101, v101, v102
	v_mul_f32_e32 v102, v134, v134
	v_mul_f32_e32 v103, v138, v138
	v_fmac_f32_e32 v102, v135, v135
	v_fmac_f32_e32 v103, v139, v139
	v_add_f32_e32 v102, v103, v102
	v_add_f32_e32 v101, v102, v101
	v_add_f32_e32 v100, v100, v101
	v_mov_b32_e32 v101, v100
	s_nop 1
	v_permlane16_swap_b32_e32 v101, v100
	s_waitcnt lgkmcnt(0)
	v_add_f32_e32 v100, v100, v101
	v_mov_b32_e32 v101, v100
	s_nop 1
	v_permlane32_swap_b32_e32 v101, v100
	s_and_saveexec_b64 s[4:5], s[38:39]
	s_cbranch_execz .LBB0_446
	v_readlane_b32 s6, v254, 60
	v_readlane_b32 s7, v254, 61
	s_lshl_b32 s8, s79, 2
	s_waitcnt lgkmcnt(0)
	v_add_f32_e32 v100, v100, v101
	v_lshl_add_u64 v[102:103], s[6:7], 0, v[202:203]
	v_readlane_b32 s6, v254, 4
	v_readlane_b32 s7, v254, 5
	v_lshl_add_u64 v[102:103], s[0:1], 2, v[102:103]
	s_mov_b32 s9, s7
	v_writelane_b32 v254, s6, 4
	v_lshl_add_u64 v[102:103], v[102:103], 0, s[8:9]
	global_store_dword v[102:103], v100, off
	v_writelane_b32 v254, s7, 5

.LBB0_450:
	s_nop 1
	v_mul_f32_e32 v84, v99, v99
	v_mul_f32_e32 v85, v96, v96
	v_fmac_f32_e32 v84, v98, v98
	v_fmac_f32_e32 v85, v97, v97
	v_add_f32_e32 v84, v84, v85
	v_mul_f32_e32 v85, v94, v94
	v_mul_f32_e32 v86, v92, v92
	v_fmac_f32_e32 v85, v95, v95
	v_fmac_f32_e32 v86, v93, v93
	v_add_f32_e32 v85, v86, v85
	v_add_f32_e32 v84, v85, v84
	v_mul_f32_e32 v85, v121, v121
	v_mul_f32_e32 v86, v116, v116
	v_fmac_f32_e32 v85, v120, v120
	v_fmac_f32_e32 v86, v117, v117
	v_add_f32_e32 v85, v85, v86
	v_mul_f32_e32 v86, v118, v118
	v_mul_f32_e32 v87, v122, v122
	v_fmac_f32_e32 v86, v119, v119
	v_fmac_f32_e32 v87, v123, v123
	v_add_f32_e32 v86, v87, v86
	v_add_f32_e32 v85, v86, v85
	v_add_f32_e32 v84, v84, v85
	v_mov_b32_e32 v85, v84
	s_nop 1
	v_permlane16_swap_b32_e32 v85, v84
	s_waitcnt lgkmcnt(0)
	v_add_f32_e32 v84, v84, v85
	v_mov_b32_e32 v85, v84
	s_nop 1
	v_permlane32_swap_b32_e32 v85, v84
	s_and_saveexec_b64 s[4:5], s[38:39]
	s_cbranch_execz .LBB0_452
	v_readlane_b32 s6, v254, 60
	v_readlane_b32 s7, v254, 61
	s_lshl_b32 s8, s79, 2
	s_waitcnt lgkmcnt(0)
	v_add_f32_e32 v84, v84, v85
	v_lshl_add_u64 v[86:87], s[6:7], 0, v[204:205]
	v_readlane_b32 s6, v254, 4
	v_readlane_b32 s7, v254, 5
	v_lshl_add_u64 v[86:87], s[0:1], 2, v[86:87]
	s_mov_b32 s9, s7
	v_writelane_b32 v254, s6, 4
	v_lshl_add_u64 v[86:87], v[86:87], 0, s[8:9]
	global_store_dword v[86:87], v84, off
	v_writelane_b32 v254, s7, 5

.LBB0_456:
	s_nop 1
	v_mul_f32_e32 v68, v113, v113
	v_mul_f32_e32 v69, v108, v108
	v_fmac_f32_e32 v68, v112, v112
	v_fmac_f32_e32 v69, v109, v109
	v_add_f32_e32 v68, v68, v69
	v_mul_f32_e32 v69, v110, v110
	v_mul_f32_e32 v70, v114, v114
	v_fmac_f32_e32 v69, v111, v111
	v_fmac_f32_e32 v70, v115, v115
	v_add_f32_e32 v69, v70, v69
	v_add_f32_e32 v68, v69, v68
	v_mul_f32_e32 v69, v105, v105
	v_mul_f32_e32 v70, v100, v100
	v_fmac_f32_e32 v69, v104, v104
	v_fmac_f32_e32 v70, v101, v101
	v_add_f32_e32 v69, v69, v70
	v_mul_f32_e32 v70, v102, v102
	v_mul_f32_e32 v71, v106, v106
	v_fmac_f32_e32 v70, v103, v103
	v_fmac_f32_e32 v71, v107, v107
	v_add_f32_e32 v70, v71, v70
	v_add_f32_e32 v69, v70, v69
	v_add_f32_e32 v68, v68, v69
	v_mov_b32_e32 v69, v68
	s_nop 1
	v_permlane16_swap_b32_e32 v69, v68
	s_waitcnt lgkmcnt(0)
	v_add_f32_e32 v68, v68, v69
	v_mov_b32_e32 v69, v68
	s_nop 1
	v_permlane32_swap_b32_e32 v69, v68
	s_and_saveexec_b64 s[4:5], s[38:39]
	s_cbranch_execz .LBB0_458
	v_readlane_b32 s6, v254, 60
	v_readlane_b32 s7, v254, 61
	s_lshl_b32 s8, s79, 2
	s_waitcnt lgkmcnt(0)
	v_add_f32_e32 v68, v68, v69
	v_lshl_add_u64 v[70:71], s[6:7], 0, v[206:207]
	v_readlane_b32 s6, v254, 4
	v_readlane_b32 s7, v254, 5
	v_lshl_add_u64 v[70:71], s[0:1], 2, v[70:71]
	s_mov_b32 s9, s7
	v_writelane_b32 v254, s6, 4
	v_lshl_add_u64 v[70:71], v[70:71], 0, s[8:9]
	global_store_dword v[70:71], v68, off
	v_writelane_b32 v254, s7, 5

.LBB0_462:
	s_nop 1
	v_mul_f32_e32 v52, v67, v67
	v_mul_f32_e32 v53, v64, v64
	v_fmac_f32_e32 v52, v66, v66
	v_fmac_f32_e32 v53, v65, v65
	v_add_f32_e32 v52, v52, v53
	v_mul_f32_e32 v53, v62, v62
	v_mul_f32_e32 v54, v60, v60
	v_fmac_f32_e32 v53, v63, v63
	v_fmac_f32_e32 v54, v61, v61
	v_add_f32_e32 v53, v54, v53
	v_add_f32_e32 v52, v53, v52
	v_mul_f32_e32 v53, v89, v89
	v_mul_f32_e32 v54, v84, v84
	v_fmac_f32_e32 v53, v88, v88
	v_fmac_f32_e32 v54, v85, v85
	v_add_f32_e32 v53, v53, v54
	v_mul_f32_e32 v54, v86, v86
	v_mul_f32_e32 v55, v90, v90
	v_fmac_f32_e32 v54, v87, v87
	v_fmac_f32_e32 v55, v91, v91
	v_add_f32_e32 v54, v55, v54
	v_add_f32_e32 v53, v54, v53
	v_add_f32_e32 v52, v52, v53
	v_mov_b32_e32 v53, v52
	s_nop 1
	v_permlane16_swap_b32_e32 v53, v52
	s_waitcnt lgkmcnt(0)
	v_add_f32_e32 v52, v52, v53
	v_mov_b32_e32 v53, v52
	s_nop 1
	v_permlane32_swap_b32_e32 v53, v52
	s_and_saveexec_b64 s[4:5], s[38:39]
	s_cbranch_execz .LBB0_464
	v_readlane_b32 s6, v254, 60
	v_readlane_b32 s7, v254, 61
	s_lshl_b32 s8, s79, 2
	s_waitcnt lgkmcnt(0)
	v_add_f32_e32 v52, v52, v53
	v_lshl_add_u64 v[54:55], s[6:7], 0, v[208:209]
	v_readlane_b32 s6, v254, 4
	v_readlane_b32 s7, v254, 5
	v_lshl_add_u64 v[54:55], s[0:1], 2, v[54:55]
	s_mov_b32 s9, s7
	v_writelane_b32 v254, s6, 4
	v_lshl_add_u64 v[54:55], v[54:55], 0, s[8:9]
	global_store_dword v[54:55], v52, off
	v_writelane_b32 v254, s7, 5

.LBB0_468:
	s_nop 1
	v_mul_f32_e32 v36, v81, v81
	v_mul_f32_e32 v37, v76, v76
	v_fmac_f32_e32 v36, v80, v80
	v_fmac_f32_e32 v37, v77, v77
	v_add_f32_e32 v36, v36, v37
	v_mul_f32_e32 v37, v78, v78
	v_mul_f32_e32 v38, v82, v82
	v_fmac_f32_e32 v37, v79, v79
	v_fmac_f32_e32 v38, v83, v83
	v_add_f32_e32 v37, v38, v37
	v_add_f32_e32 v36, v37, v36
	v_mul_f32_e32 v37, v73, v73
	v_mul_f32_e32 v38, v68, v68
	v_fmac_f32_e32 v37, v72, v72
	v_fmac_f32_e32 v38, v69, v69
	v_add_f32_e32 v37, v37, v38
	v_mul_f32_e32 v38, v70, v70
	v_mul_f32_e32 v39, v74, v74
	v_fmac_f32_e32 v38, v71, v71
	v_fmac_f32_e32 v39, v75, v75
	v_add_f32_e32 v38, v39, v38
	v_add_f32_e32 v37, v38, v37
	v_add_f32_e32 v36, v36, v37
	v_mov_b32_e32 v37, v36
	s_nop 1
	v_permlane16_swap_b32_e32 v37, v36
	s_waitcnt lgkmcnt(0)
	v_add_f32_e32 v36, v36, v37
	v_mov_b32_e32 v37, v36
	s_nop 1
	v_permlane32_swap_b32_e32 v37, v36
	s_and_saveexec_b64 s[4:5], s[38:39]
	s_cbranch_execz .LBB0_470
	v_readlane_b32 s6, v254, 60
	v_readlane_b32 s7, v254, 61
	s_lshl_b32 s8, s79, 2
	s_waitcnt lgkmcnt(0)
	v_add_f32_e32 v36, v36, v37
	v_lshl_add_u64 v[38:39], s[6:7], 0, v[210:211]
	v_readlane_b32 s6, v254, 4
	v_readlane_b32 s7, v254, 5
	v_lshl_add_u64 v[38:39], s[0:1], 2, v[38:39]
	s_mov_b32 s9, s7
	v_writelane_b32 v254, s6, 4
	v_lshl_add_u64 v[38:39], v[38:39], 0, s[8:9]
	global_store_dword v[38:39], v36, off
	v_writelane_b32 v254, s7, 5

.LBB0_474:
	s_nop 1
	v_mul_f32_e32 v52, v35, v35
	v_mul_f32_e32 v53, v32, v32
	v_fmac_f32_e32 v52, v34, v34
	v_fmac_f32_e32 v53, v33, v33
	v_add_f32_e32 v52, v52, v53
	v_mul_f32_e32 v53, v30, v30
	v_mul_f32_e32 v54, v28, v28
	v_fmac_f32_e32 v53, v31, v31
	v_fmac_f32_e32 v54, v29, v29
	v_add_f32_e32 v53, v54, v53
	v_add_f32_e32 v52, v53, v52
	v_mul_f32_e32 v53, v23, v23
	v_mul_f32_e32 v54, v20, v20
	v_fmac_f32_e32 v53, v22, v22
	v_fmac_f32_e32 v54, v21, v21
	v_add_f32_e32 v53, v53, v54
	v_mul_f32_e32 v54, v24, v24
	v_mul_f32_e32 v55, v26, v26
	v_fmac_f32_e32 v54, v25, v25
	v_fmac_f32_e32 v55, v27, v27
	v_add_f32_e32 v54, v55, v54
	v_add_f32_e32 v53, v54, v53
	v_add_f32_e32 v52, v52, v53
	v_mov_b32_e32 v53, v52
	s_nop 1
	v_permlane16_swap_b32_e32 v53, v52
	s_waitcnt lgkmcnt(0)
	v_add_f32_e32 v52, v52, v53
	v_mov_b32_e32 v53, v52
	s_nop 1
	v_permlane32_swap_b32_e32 v53, v52
	s_and_saveexec_b64 s[4:5], s[38:39]
	s_cbranch_execz .LBB0_476
	v_readlane_b32 s6, v254, 60
	v_readlane_b32 s7, v254, 61
	s_lshl_b32 s8, s79, 2
	s_waitcnt lgkmcnt(0)
	v_add_f32_e32 v52, v52, v53
	v_lshl_add_u64 v[54:55], s[6:7], 0, v[212:213]
	v_readlane_b32 s6, v254, 4
	v_readlane_b32 s7, v254, 5
	v_lshl_add_u64 v[54:55], s[0:1], 2, v[54:55]
	s_mov_b32 s9, s7
	v_writelane_b32 v254, s6, 4
	v_lshl_add_u64 v[54:55], v[54:55], 0, s[8:9]
	global_store_dword v[54:55], v52, off
	v_writelane_b32 v254, s7, 5

.LBB0_480:
	s_nop 1
	v_mul_f32_e32 v4, v49, v49
	v_mul_f32_e32 v5, v44, v44
	v_fmac_f32_e32 v4, v48, v48
	v_fmac_f32_e32 v5, v45, v45
	v_add_f32_e32 v4, v4, v5
	v_mul_f32_e32 v5, v46, v46
	v_mul_f32_e32 v6, v50, v50
	v_fmac_f32_e32 v5, v47, v47
	v_fmac_f32_e32 v6, v51, v51
	v_add_f32_e32 v5, v6, v5
	v_add_f32_e32 v4, v5, v4
	v_mul_f32_e32 v5, v41, v41
	v_mul_f32_e32 v6, v36, v36
	v_fmac_f32_e32 v5, v40, v40
	v_fmac_f32_e32 v6, v37, v37
	v_add_f32_e32 v5, v5, v6
	v_mul_f32_e32 v6, v38, v38
	v_mul_f32_e32 v7, v42, v42
	v_fmac_f32_e32 v6, v39, v39
	v_fmac_f32_e32 v7, v43, v43
	v_add_f32_e32 v6, v7, v6
	v_add_f32_e32 v5, v6, v5
	v_add_f32_e32 v4, v4, v5
	v_mov_b32_e32 v5, v4
	s_nop 1
	v_permlane16_swap_b32_e32 v5, v4
	s_waitcnt lgkmcnt(0)
	v_add_f32_e32 v4, v4, v5
	v_mov_b32_e32 v5, v4
	s_nop 1
	v_permlane32_swap_b32_e32 v5, v4
	s_and_saveexec_b64 s[4:5], s[38:39]
	s_cbranch_execz .LBB0_482
	v_readlane_b32 s6, v254, 60
	v_readlane_b32 s7, v254, 61
	s_waitcnt lgkmcnt(0)
	v_add_f32_e32 v4, v4, v5
	v_lshl_add_u64 v[6:7], s[6:7], 0, v[214:215]
	v_lshl_add_u64 v[6:7], s[0:1], 2, v[6:7]
	v_readlane_b32 s0, v254, 4
	v_readlane_b32 s1, v254, 5
	s_mov_b32 s7, s1
	s_lshl_b32 s6, s79, 2
	v_writelane_b32 v254, s0, 4
	v_lshl_add_u64 v[6:7], v[6:7], 0, s[6:7]
	global_store_dword v[6:7], v4, off
	v_writelane_b32 v254, s1, 5

; template <class Sh> __device__ __forceinline__ void pl_final_tail(const EpiRes<1>& E, Acc& acc, const Unit& u, int wr, int wc, int fr, int fq, const Sh& sh) {
;     ...
;     const int cb = u.pn * 256 + wc * 32 + 8 * fq, lane = fq * 16 + fr, grow = u.pm * 256 + wr * 64 + fr;
;     float rsf[2][4];
;     load_rs8(rsf, (const float*)E.ssout, fq, lane, sh, [&](int ai, int m) { return grow + ai * 128 + m * 16; });
;     f32x4 g[2][2];
; #pragma unroll
;     for (int bj = 0; bj < 2; ++bj) { g[bj][0] = *(const f32x4*)(E.gfin + cb + bj * 128); g[bj][1] = *(const f32x4*)(E.gfin + cb + bj * 128 + 4); }
.LBB0_554:
	s_or_b64 exec, exec, s[4:5]
	s_waitcnt lgkmcnt(0)
	v_lshl_add_u64 v[4:5], v[172:173], 0, v[200:201]
	s_barrier
	global_load_dwordx4 v[4:7], v[4:5], off
	v_lshl_add_u64 v[8:9], v[172:173], 0, v[202:203]
	global_load_dwordx4 v[8:11], v[8:9], off
	v_lshl_add_u64 v[12:13], v[172:173], 0, v[204:205]
	global_load_dwordx4 v[12:15], v[12:13], off
	v_lshl_add_u64 v[16:17], v[172:173], 0, v[206:207]
	global_load_dwordx4 v[16:19], v[16:17], off
	v_lshl_add_u64 v[52:53], v[172:173], 0, v[208:209]
	global_load_dwordx4 v[52:55], v[52:53], off
	v_lshl_add_u64 v[56:57], v[172:173], 0, v[210:211]
	global_load_dwordx4 v[200:203], v[56:57], off
	v_lshl_add_u64 v[56:57], v[172:173], 0, v[212:213]
	global_load_dwordx4 v[204:207], v[56:57], off
	v_lshl_add_u64 v[56:57], v[172:173], 0, v[214:215]
	global_load_dwordx4 v[208:211], v[56:57], off
	v_lshlrev_b64 v[198:199], 2, v[198:199]
	v_lshlrev_b64 v[192:193], 12, v[192:193]
	v_lshl_add_u64 v[192:193], s[72:73], 0, v[192:193]
	v_lshl_add_u64 v[192:193], v[192:193], 0, v[198:199]
	s_waitcnt vmcnt(7)
	v_mov_b32_e32 v56, v5
	v_mov_b32_e32 v57, v6
	v_mov_b32_e32 v5, v7
	v_pk_add_f32 v[4:5], v[56:57], v[4:5]
	s_nop 0
	v_add_f32_e32 v4, v4, v5
	v_mov_b32_e32 v5, v4
	s_nop 1
	v_permlane16_swap_b32_e32 v5, v4
	s_waitcnt lgkmcnt(0)
	v_add_f32_e32 v4, v4, v5
	v_mov_b32_e32 v5, v4
	s_nop 1
	v_permlane32_swap_b32_e32 v5, v4
	s_waitcnt lgkmcnt(0)
	v_add_f32_e32 v4, v4, v5
	v_fmamk_f32 v4, v4, 0x3a800000, v226
	v_rsq_f32_e32 v162, v4
	s_waitcnt vmcnt(6)
	v_mov_b32_e32 v4, v9
	v_mov_b32_e32 v5, v10
	v_mov_b32_e32 v9, v11
	v_pk_add_f32 v[4:5], v[4:5], v[8:9]
	v_lshl_add_u64 v[8:9], s[70:71], 0, v[198:199]
	v_add_f32_e32 v4, v4, v5
	v_mov_b32_e32 v5, v4
	s_nop 1
	v_permlane16_swap_b32_e32 v5, v4
	v_pk_mul_f32 v[194:195], v[126:127], v[162:163] op_sel_hi:[1,0]
	v_pk_mul_f32 v[124:125], v[124:125], v[162:163] op_sel_hi:[1,0]
	s_waitcnt lgkmcnt(0)
	v_add_f32_e32 v4, v4, v5
	v_mov_b32_e32 v5, v4
	s_nop 1
	v_permlane32_swap_b32_e32 v5, v4
	s_waitcnt lgkmcnt(0)
	v_add_f32_e32 v4, v4, v5
	v_fmamk_f32 v4, v4, 0x3a800000, v226
	v_rsq_f32_e32 v160, v4
	s_waitcnt vmcnt(5)
	v_mov_b32_e32 v4, v13
	v_mov_b32_e32 v5, v14
	v_mov_b32_e32 v13, v15
	v_pk_add_f32 v[4:5], v[4:5], v[12:13]
	s_nop 0
	v_add_f32_e32 v4, v4, v5
	v_mov_b32_e32 v5, v4
	s_nop 1
	v_permlane16_swap_b32_e32 v5, v4
	s_waitcnt lgkmcnt(0)
	v_add_f32_e32 v4, v4, v5
	v_mov_b32_e32 v5, v4
	s_nop 1
	v_permlane32_swap_b32_e32 v5, v4
	s_waitcnt lgkmcnt(0)
	v_add_f32_e32 v4, v4, v5
	v_fmamk_f32 v4, v4, 0x3a800000, v226
	v_rsq_f32_e32 v158, v4
	s_waitcnt vmcnt(4)
	v_mov_b32_e32 v4, v17
	v_mov_b32_e32 v5, v18
	v_mov_b32_e32 v17, v19
	v_pk_add_f32 v[4:5], v[4:5], v[16:17]
	v_pk_mul_f32 v[96:97], v[96:97], v[158:159] op_sel_hi:[1,0]
	v_add_f32_e32 v4, v4, v5
	v_mov_b32_e32 v5, v4
	s_nop 1
	v_permlane16_swap_b32_e32 v5, v4
	v_pk_mul_f32 v[92:93], v[92:93], v[158:159] op_sel_hi:[1,0]
	s_waitcnt lgkmcnt(0)
	v_add_f32_e32 v4, v4, v5
	v_mov_b32_e32 v5, v4
	s_nop 1
	v_permlane32_swap_b32_e32 v5, v4
	s_waitcnt lgkmcnt(0)
	v_add_f32_e32 v4, v4, v5
	v_fmamk_f32 v4, v4, 0x3a800000, v226
	v_rsq_f32_e32 v156, v4
	s_waitcnt vmcnt(3)
	v_mov_b32_e32 v4, v53
	v_mov_b32_e32 v5, v54
	v_mov_b32_e32 v53, v55
	v_pk_add_f32 v[4:5], v[4:5], v[52:53]
	s_nop 0
	v_add_f32_e32 v4, v4, v5
	v_mov_b32_e32 v5, v4
	s_nop 1
	v_permlane16_swap_b32_e32 v5, v4
	s_waitcnt lgkmcnt(0)
	v_add_f32_e32 v4, v4, v5
	v_mov_b32_e32 v5, v4
	s_nop 1
	v_permlane32_swap_b32_e32 v5, v4
	s_waitcnt lgkmcnt(0)
	v_add_f32_e32 v4, v4, v5
	v_fmamk_f32 v4, v4, 0x3a800000, v226
	v_rsq_f32_e32 v58, v4
	s_waitcnt vmcnt(2)
	v_mov_b32_e32 v4, v201
	v_mov_b32_e32 v5, v202
	v_mov_b32_e32 v201, v203
	v_pk_add_f32 v[4:5], v[4:5], v[200:201]
	v_pk_mul_f32 v[64:65], v[64:65], v[58:59] op_sel_hi:[1,0]
	v_add_f32_e32 v4, v4, v5
	v_mov_b32_e32 v5, v4
	s_nop 1
	v_permlane16_swap_b32_e32 v5, v4
	v_pk_mul_f32 v[60:61], v[60:61], v[58:59] op_sel_hi:[1,0]
	s_waitcnt lgkmcnt(0)
	v_add_f32_e32 v4, v4, v5
	v_mov_b32_e32 v5, v4
	s_nop 1
	v_permlane32_swap_b32_e32 v5, v4
	s_waitcnt lgkmcnt(0)
	v_add_f32_e32 v4, v4, v5
	v_fmamk_f32 v4, v4, 0x3a800000, v226
	v_rsq_f32_e32 v56, v4
	s_waitcnt vmcnt(1)
	v_mov_b32_e32 v4, v205
	v_mov_b32_e32 v5, v206
	v_mov_b32_e32 v205, v207
	v_pk_add_f32 v[4:5], v[4:5], v[204:205]
	s_nop 0
	v_add_f32_e32 v4, v4, v5
	v_mov_b32_e32 v5, v4
	s_nop 1
	v_permlane16_swap_b32_e32 v5, v4
	s_waitcnt lgkmcnt(0)
	v_add_f32_e32 v4, v4, v5
	v_mov_b32_e32 v5, v4
	s_nop 1
	v_permlane32_swap_b32_e32 v5, v4
	s_waitcnt lgkmcnt(0)
	v_add_f32_e32 v4, v4, v5
	v_fmamk_f32 v4, v4, 0x3a800000, v226
	v_rsq_f32_e32 v54, v4
	s_waitcnt vmcnt(0)
	v_mov_b32_e32 v4, v209
	v_mov_b32_e32 v5, v210
	v_mov_b32_e32 v209, v211
	v_pk_add_f32 v[4:5], v[4:5], v[208:209]
	v_pk_mul_f32 v[32:33], v[32:33], v[54:55] op_sel_hi:[1,0]
	v_add_f32_e32 v4, v4, v5
	v_mov_b32_e32 v5, v4
	s_nop 1
	v_permlane16_swap_b32_e32 v5, v4
	v_pk_mul_f32 v[28:29], v[28:29], v[54:55] op_sel_hi:[1,0]
	v_pk_mul_f32 v[20:21], v[20:21], v[54:55] op_sel_hi:[1,0]
	s_waitcnt lgkmcnt(0)
	v_add_f32_e32 v4, v4, v5
	v_mov_b32_e32 v5, v4
	s_nop 1
	v_permlane32_swap_b32_e32 v5, v4
	s_waitcnt lgkmcnt(0)
	v_add_f32_e32 v4, v4, v5
	v_fmamk_f32 v4, v4, 0x3a800000, v226
	v_rsq_f32_e32 v52, v4
	global_load_dwordx4 v[12:15], v[8:9], off offset:16
	global_load_dwordx4 v[16:19], v[8:9], off
	global_load_dwordx4 v[4:7], v[8:9], off offset:528
	s_nop 0
	global_load_dwordx4 v[8:11], v[8:9], off offset:512
	s_waitcnt vmcnt(2)
; #define GAS __attribute__((address_space(1)))
; template <class Sh> __device__ __forceinline__ void pl_final_tail(const EpiRes<1>& E, Acc& acc, const Unit& u, int wr, int wc, int fr, int fq, const Sh& sh) {
;     ...
; #pragma unroll
;     for (int ai = 0; ai < 2; ++ai)
; #pragma unroll
;         for (int m = 0; m < 4; ++m) {
;             const float rs = rsf[ai][m];
; #pragma unroll
;             for (int bj = 0; bj < 2; ++bj) {
;                 GAS f32x4* o = (GAS f32x4*)(E.fout + (size_t)(grow + ai * 128 + m * 16) * D + cb + bj * 128);
;                 __builtin_nontemporal_store(acc[ai][bj][m][0] * rs * g[bj][0], o); __builtin_nontemporal_store(acc[ai][bj][m][1] * rs * g[bj][1], o + 1);
;             }
;         }
	v_pk_mul_f32 v[126:127], v[124:125], v[18:19]
	v_pk_mul_f32 v[124:125], v[194:195], v[16:17]
	global_store_dwordx4 v[192:193], v[124:127], off nt
	s_nop 1
	v_pk_mul_f32 v[124:125], v[128:129], v[162:163] op_sel_hi:[1,0]
	v_pk_mul_f32 v[126:127], v[130:131], v[162:163] op_sel_hi:[1,0]
	v_pk_mul_f32 v[124:125], v[124:125], v[12:13]
	v_pk_mul_f32 v[126:127], v[126:127], v[14:15]
	global_store_dwordx4 v[192:193], v[124:127], off offset:16 nt
	s_nop 1
	v_pk_mul_f32 v[124:125], v[152:153], v[162:163] op_sel_hi:[1,0]
	v_pk_mul_f32 v[126:127], v[148:149], v[162:163] op_sel_hi:[1,0]
	s_waitcnt vmcnt(2)
	v_pk_mul_f32 v[124:125], v[124:125], v[8:9]
	v_pk_mul_f32 v[126:127], v[126:127], v[10:11]
	global_store_dwordx4 v[192:193], v[124:127], off offset:512 nt
	s_nop 1
	v_pk_mul_f32 v[124:125], v[150:151], v[162:163] op_sel_hi:[1,0]
	v_pk_mul_f32 v[126:127], v[154:155], v[162:163] op_sel_hi:[1,0]
	v_pk_mul_f32 v[124:125], v[124:125], v[4:5]
	v_pk_mul_f32 v[126:127], v[126:127], v[6:7]
	global_store_dwordx4 v[192:193], v[124:127], off offset:528 nt
	s_nop 1
	v_lshlrev_b64 v[124:125], 12, v[190:191]
	v_lshl_add_u64 v[124:125], s[72:73], 0, v[124:125]
	v_lshl_add_u64 v[128:129], v[124:125], 0, v[198:199]
	v_pk_mul_f32 v[124:125], v[144:145], v[160:161] op_sel_hi:[1,0]
	v_pk_mul_f32 v[126:127], v[140:141], v[160:161] op_sel_hi:[1,0]
	v_pk_mul_f32 v[124:125], v[124:125], v[16:17]
	v_pk_mul_f32 v[126:127], v[126:127], v[18:19]
	global_store_dwordx4 v[128:129], v[124:127], off nt
	s_nop 1
	v_pk_mul_f32 v[124:125], v[142:143], v[160:161] op_sel_hi:[1,0]
	v_pk_mul_f32 v[126:127], v[146:147], v[160:161] op_sel_hi:[1,0]
	v_pk_mul_f32 v[124:125], v[124:125], v[12:13]
	v_pk_mul_f32 v[126:127], v[126:127], v[14:15]
	global_store_dwordx4 v[128:129], v[124:127], off offset:16 nt
	s_nop 1
	v_pk_mul_f32 v[124:125], v[136:137], v[160:161] op_sel_hi:[1,0]
	v_pk_mul_f32 v[126:127], v[132:133], v[160:161] op_sel_hi:[1,0]
	v_pk_mul_f32 v[124:125], v[124:125], v[8:9]
	v_pk_mul_f32 v[126:127], v[126:127], v[10:11]
	global_store_dwordx4 v[128:129], v[124:127], off offset:512 nt
	s_nop 1
	v_pk_mul_f32 v[124:125], v[134:135], v[160:161] op_sel_hi:[1,0]
	v_pk_mul_f32 v[126:127], v[138:139], v[160:161] op_sel_hi:[1,0]
	v_pk_mul_f32 v[124:125], v[124:125], v[4:5]
	v_pk_mul_f32 v[126:127], v[126:127], v[6:7]
	global_store_dwordx4 v[128:129], v[124:127], off offset:528 nt
	s_nop 1
	v_lshlrev_b64 v[124:125], 12, v[188:189]
	v_lshl_add_u64 v[124:125], s[72:73], 0, v[124:125]
	v_pk_mul_f32 v[126:127], v[98:99], v[158:159] op_sel_hi:[1,0]
	v_lshl_add_u64 v[124:125], v[124:125], 0, v[198:199]
	v_pk_mul_f32 v[98:99], v[96:97], v[18:19]
	v_pk_mul_f32 v[96:97], v[126:127], v[16:17]
	global_store_dwordx4 v[124:125], v[96:99], off nt
	s_nop 1
	v_pk_mul_f32 v[96:97], v[94:95], v[158:159] op_sel_hi:[1,0]
	v_pk_mul_f32 v[94:95], v[92:93], v[14:15]
	v_pk_mul_f32 v[92:93], v[96:97], v[12:13]
	global_store_dwordx4 v[124:125], v[92:95], off offset:16 nt
	s_nop 1
	v_pk_mul_f32 v[92:93], v[120:121], v[158:159] op_sel_hi:[1,0]
	v_pk_mul_f32 v[94:95], v[116:117], v[158:159] op_sel_hi:[1,0]
	v_pk_mul_f32 v[92:93], v[92:93], v[8:9]
	v_pk_mul_f32 v[94:95], v[94:95], v[10:11]
	global_store_dwordx4 v[124:125], v[92:95], off offset:512 nt
	s_nop 1
	v_pk_mul_f32 v[92:93], v[118:119], v[158:159] op_sel_hi:[1,0]
	v_pk_mul_f32 v[94:95], v[122:123], v[158:159] op_sel_hi:[1,0]
	v_pk_mul_f32 v[92:93], v[92:93], v[4:5]
	v_pk_mul_f32 v[94:95], v[94:95], v[6:7]
	global_store_dwordx4 v[124:125], v[92:95], off offset:528 nt
	s_nop 1
	v_lshlrev_b64 v[92:93], 12, v[186:187]
	v_lshl_add_u64 v[92:93], s[72:73], 0, v[92:93]
	v_lshl_add_u64 v[96:97], v[92:93], 0, v[198:199]
	v_pk_mul_f32 v[92:93], v[112:113], v[156:157] op_sel_hi:[1,0]
	v_pk_mul_f32 v[94:95], v[108:109], v[156:157] op_sel_hi:[1,0]
	v_pk_mul_f32 v[92:93], v[92:93], v[16:17]
	v_pk_mul_f32 v[94:95], v[94:95], v[18:19]
	global_store_dwordx4 v[96:97], v[92:95], off nt
	s_nop 1
	v_pk_mul_f32 v[92:93], v[110:111], v[156:157] op_sel_hi:[1,0]
	v_pk_mul_f32 v[94:95], v[114:115], v[156:157] op_sel_hi:[1,0]
	v_pk_mul_f32 v[92:93], v[92:93], v[12:13]
	v_pk_mul_f32 v[94:95], v[94:95], v[14:15]
	global_store_dwordx4 v[96:97], v[92:95], off offset:16 nt
	s_nop 1
	v_pk_mul_f32 v[92:93], v[104:105], v[156:157] op_sel_hi:[1,0]
	v_pk_mul_f32 v[94:95], v[100:101], v[156:157] op_sel_hi:[1,0]
	v_pk_mul_f32 v[92:93], v[92:93], v[8:9]
	v_pk_mul_f32 v[94:95], v[94:95], v[10:11]
	global_store_dwordx4 v[96:97], v[92:95], off offset:512 nt
	s_nop 1
	v_pk_mul_f32 v[92:93], v[102:103], v[156:157] op_sel_hi:[1,0]
	v_pk_mul_f32 v[94:95], v[106:107], v[156:157] op_sel_hi:[1,0]
	v_pk_mul_f32 v[92:93], v[92:93], v[4:5]
; #define GAS __attribute__((address_space(1)))
; template <class Sh> __device__ __forceinline__ void pl_final_tail(const EpiRes<1>& E, Acc& acc, const Unit& u, int wr, int wc, int fr, int fq, const Sh& sh) {
;     ...
; #pragma unroll
;     for (int ai = 0; ai < 2; ++ai)
; #pragma unroll
;         for (int m = 0; m < 4; ++m) {
;             const float rs = rsf[ai][m];
; #pragma unroll
;             for (int bj = 0; bj < 2; ++bj) {
;                 GAS f32x4* o = (GAS f32x4*)(E.fout + (size_t)(grow + ai * 128 + m * 16) * D + cb + bj * 128);
;                 __builtin_nontemporal_store(acc[ai][bj][m][0] * rs * g[bj][0], o); __builtin_nontemporal_store(acc[ai][bj][m][1] * rs * g[bj][1], o + 1);
;             }
;         }
	v_pk_mul_f32 v[94:95], v[94:95], v[6:7]
	global_store_dwordx4 v[96:97], v[92:95], off offset:528 nt
	s_nop 1
	v_lshlrev_b64 v[92:93], 12, v[184:185]
	v_lshl_add_u64 v[92:93], s[72:73], 0, v[92:93]
	v_pk_mul_f32 v[94:95], v[66:67], v[58:59] op_sel_hi:[1,0]
	v_lshl_add_u64 v[92:93], v[92:93], 0, v[198:199]
	v_pk_mul_f32 v[66:67], v[18:19], v[64:65]
	v_pk_mul_f32 v[64:65], v[16:17], v[94:95]
	global_store_dwordx4 v[92:93], v[64:67], off nt
	s_nop 1
	v_pk_mul_f32 v[64:65], v[62:63], v[58:59] op_sel_hi:[1,0]
	v_pk_mul_f32 v[62:63], v[14:15], v[60:61]
	v_pk_mul_f32 v[60:61], v[12:13], v[64:65]
	global_store_dwordx4 v[92:93], v[60:63], off offset:16 nt
	s_nop 1
	v_pk_mul_f32 v[60:61], v[88:89], v[58:59] op_sel_hi:[1,0]
	v_pk_mul_f32 v[62:63], v[84:85], v[58:59] op_sel_hi:[1,0]
	v_pk_mul_f32 v[60:61], v[60:61], v[8:9]
	v_pk_mul_f32 v[62:63], v[62:63], v[10:11]
	global_store_dwordx4 v[92:93], v[60:63], off offset:512 nt
	s_nop 1
	v_pk_mul_f32 v[62:63], v[86:87], v[58:59] op_sel_hi:[1,0]
	v_pk_mul_f32 v[58:59], v[90:91], v[58:59] op_sel_hi:[1,0]
	s_nop 0
	v_pk_mul_f32 v[60:61], v[58:59], v[6:7]
	v_pk_mul_f32 v[58:59], v[62:63], v[4:5]
	global_store_dwordx4 v[92:93], v[58:61], off offset:528 nt
	s_nop 1
	v_lshlrev_b64 v[58:59], 12, v[182:183]
	v_lshl_add_u64 v[58:59], s[72:73], 0, v[58:59]
	v_lshl_add_u64 v[62:63], v[58:59], 0, v[198:199]
	v_pk_mul_f32 v[58:59], v[80:81], v[56:57] op_sel_hi:[1,0]
	v_pk_mul_f32 v[60:61], v[76:77], v[56:57] op_sel_hi:[1,0]
	v_pk_mul_f32 v[58:59], v[16:17], v[58:59]
	v_pk_mul_f32 v[60:61], v[18:19], v[60:61]
	global_store_dwordx4 v[62:63], v[58:61], off nt
	s_nop 1
	v_pk_mul_f32 v[58:59], v[78:79], v[56:57] op_sel_hi:[1,0]
	v_pk_mul_f32 v[60:61], v[82:83], v[56:57] op_sel_hi:[1,0]
	v_pk_mul_f32 v[58:59], v[12:13], v[58:59]
	v_pk_mul_f32 v[60:61], v[14:15], v[60:61]
	global_store_dwordx4 v[62:63], v[58:61], off offset:16 nt
	s_nop 1
	v_pk_mul_f32 v[58:59], v[72:73], v[56:57] op_sel_hi:[1,0]
	v_pk_mul_f32 v[60:61], v[68:69], v[56:57] op_sel_hi:[1,0]
	v_pk_mul_f32 v[58:59], v[8:9], v[58:59]
	v_pk_mul_f32 v[60:61], v[10:11], v[60:61]
	global_store_dwordx4 v[62:63], v[58:61], off offset:512 nt
	s_nop 1
	v_pk_mul_f32 v[60:61], v[70:71], v[56:57] op_sel_hi:[1,0]
	v_pk_mul_f32 v[56:57], v[74:75], v[56:57] op_sel_hi:[1,0]
	s_nop 0
	v_pk_mul_f32 v[58:59], v[6:7], v[56:57]
	v_pk_mul_f32 v[56:57], v[4:5], v[60:61]
	global_store_dwordx4 v[62:63], v[56:59], off offset:528 nt
	s_nop 1
	v_lshlrev_b64 v[56:57], 12, v[180:181]
	v_lshl_add_u64 v[56:57], s[72:73], 0, v[56:57]
	v_pk_mul_f32 v[58:59], v[34:35], v[54:55] op_sel_hi:[1,0]
	v_lshl_add_u64 v[56:57], v[56:57], 0, v[198:199]
	v_pk_mul_f32 v[34:35], v[18:19], v[32:33]
	v_pk_mul_f32 v[32:33], v[16:17], v[58:59]
	global_store_dwordx4 v[56:57], v[32:35], off nt
	s_nop 1
	v_pk_mul_f32 v[32:33], v[30:31], v[54:55] op_sel_hi:[1,0]
	v_pk_mul_f32 v[30:31], v[14:15], v[28:29]
	v_pk_mul_f32 v[28:29], v[12:13], v[32:33]
	global_store_dwordx4 v[56:57], v[28:31], off offset:16 nt
	s_nop 1
	v_pk_mul_f32 v[28:29], v[22:23], v[54:55] op_sel_hi:[1,0]
	v_pk_mul_f32 v[22:23], v[10:11], v[20:21]
	v_pk_mul_f32 v[20:21], v[8:9], v[28:29]
	global_store_dwordx4 v[56:57], v[20:23], off offset:512 nt
	s_nop 1
	v_pk_mul_f32 v[20:21], v[24:25], v[54:55] op_sel_hi:[1,0]
	v_pk_mul_f32 v[22:23], v[26:27], v[54:55] op_sel_hi:[1,0]
	v_pk_mul_f32 v[20:21], v[4:5], v[20:21]
	v_pk_mul_f32 v[22:23], v[6:7], v[22:23]
	global_store_dwordx4 v[56:57], v[20:23], off offset:528 nt
	v_pk_mul_f32 v[24:25], v[44:45], v[52:53] op_sel_hi:[1,0]
	s_nop 0
	v_lshlrev_b64 v[20:21], 12, v[178:179]
	v_lshl_add_u64 v[20:21], s[72:73], 0, v[20:21]
	v_pk_mul_f32 v[22:23], v[48:49], v[52:53] op_sel_hi:[1,0]
	v_lshl_add_u64 v[20:21], v[20:21], 0, v[198:199]
	v_pk_mul_f32 v[18:19], v[18:19], v[24:25]
	v_pk_mul_f32 v[16:17], v[16:17], v[22:23]
	global_store_dwordx4 v[20:21], v[16:19], off nt
	s_nop 1
	v_pk_mul_f32 v[16:17], v[46:47], v[52:53] op_sel_hi:[1,0]
	v_pk_mul_f32 v[18:19], v[50:51], v[52:53] op_sel_hi:[1,0]
	v_pk_mul_f32 v[12:13], v[12:13], v[16:17]
	v_pk_mul_f32 v[14:15], v[14:15], v[18:19]
	global_store_dwordx4 v[20:21], v[12:15], off offset:16 nt
	s_nop 1
	v_pk_mul_f32 v[12:13], v[40:41], v[52:53] op_sel_hi:[1,0]
	v_pk_mul_f32 v[14:15], v[36:37], v[52:53] op_sel_hi:[1,0]
	v_pk_mul_f32 v[8:9], v[8:9], v[12:13]
	v_pk_mul_f32 v[10:11], v[10:11], v[14:15]
	global_store_dwordx4 v[20:21], v[8:11], off offset:512 nt
	s_nop 1
	v_pk_mul_f32 v[8:9], v[38:39], v[52:53] op_sel_hi:[1,0]
	v_pk_mul_f32 v[10:11], v[42:43], v[52:53] op_sel_hi:[1,0]
	v_pk_mul_f32 v[4:5], v[4:5], v[8:9]
	v_pk_mul_f32 v[6:7], v[6:7], v[10:11]
	global_store_dwordx4 v[20:21], v[4:7], off offset:528 nt
